# v49 + small sample-row GEMM units: next K-tile LDS stores issued before the MFMA block (compute waves go MFMA to barrier directly)
# speedup vs baseline: 1.0060x; 1.0000x over previous
; #define LAS __attribute__((address_space(3)))
; template <int ROWS> DI void gs_load(GsRegs<ROWS>& R, const bf16* ap, const bf16* bp, int K, int kt) {
; #pragma unroll
;     for (int rep = 0; rep < ROWS / 64; ++rep) R.a[rep] = *(const u32x4*)(ap + (size_t)(64 * rep) * K + kt * 64);
;     R.b = *(const u32x4*)(bp + kt * 64);
; }
; template <int ROWS> DI void gs_store(const GsRegs<ROWS>& R, LAS unsigned char* buf, int soff) {
; #pragma unroll
;     for (int rep = 0; rep < ROWS / 64; ++rep) *(LAS u32x4*)(buf + soff + rep * (64 * GS_LD * 2)) = R.a[rep];
;     *(LAS u32x4*)(buf + ROWS * GS_LD * 2 + soff) = R.b;
; }
; template <int ROWS> DI void gs_compute(f32x16& acc0, f32x16& acc1, const LAS unsigned char* ab, int wave, int r, int h2) {
;     const LAS unsigned char* bb = ab + ROWS * GS_LD * 2;
; #pragma unroll
;     for (int s = 0; s < 4; ++s) {
;         const bf16x8 a = *(const LAS bf16x8*)(ab + ((32 * wave + r) * GS_LD + 16 * s + 8 * h2) * 2);
;         const bf16x8 b0 = *(const LAS bf16x8*)(bb + (r * GS_LD + 16 * s + 8 * h2) * 2), b1 = *(const LAS bf16x8*)(bb + ((32 + r) * GS_LD + 16 * s + 8 * h2) * 2);
;         acc0 = MFMA32(a, b0, acc0); acc1 = MFMA32(a, b1, acc1);
;     }
; }
; template <int ROWS, class Epi> DI void gemm_small_unit(LAS unsigned char* lds, const bf16* A, const bf16* Bt, int K, int m0, int n0, int n1, const Epi& E, int tid_, int wave) {
;     constexpr int BUF = (ROWS + 64) * GS_LD * 2;
;     int tid = tid_; asm volatile("" : "+v"(tid));
;     const int lane = tid & 63, r = lane & 31, h2 = lane >> 5;
;     const int arow = tid >> 3, ck = tid & 7;
;     const bf16* ap = A + (size_t)(m0 + arow) * K + ck * 8;
;     const bf16* bp = Bt + (size_t)(arow < 32 ? n0 + arow : n1 + arow - 32) * K + ck * 8;
;     const int soff = (arow * GS_LD + ck * 8) * 2;
;     f32x16 acc0, acc1;
; #pragma unroll
;     for (int i = 0; i < 16; ++i) { acc0[i] = 0.f; acc1[i] = 0.f; }
;     GsRegs<ROWS> R0, R1, R2, R3;
;     gs_load<ROWS>(R0, ap, bp, K, 0); gs_load<ROWS>(R1, ap, bp, K, 1); gs_load<ROWS>(R2, ap, bp, K, 2); gs_load<ROWS>(R3, ap, bp, K, 3);
;     gs_store<ROWS>(R0, lds, soff);
;     __syncthreads();
;     const int nkt = K >> 6;
;     ...
; #pragma unroll 1
;     for (int kt = 0; kt < nkt; kt += 4) { GS_STEP(R0, R1, kt); GS_STEP(R1, R2, kt + 1); GS_STEP(R2, R3, kt + 2); GS_STEP(R3, R0, kt + 3); }
.LBB0_163:
	s_add_i32 s22, s22, 4
	s_addk_i32 s21, 0x100
	s_and_b64 vcc, exec, s[16:17]
	s_waitcnt lgkmcnt(0)
	s_barrier
	s_cbranch_vccnz .LBB0_172
.LBB0_164:
	s_cmp_gt_u32 s22, 11
	s_cselect_b64 s[16:17], -1, 0
	s_cmp_lt_u32 s22, 12
	s_cselect_b32 s14, s21, 0x3c0
	s_lshl_b64 s[4:5], s[14:15], 1
	v_lshl_add_u64 v[72:73], v[84:85], 0, s[4:5]
	v_add_co_u32_e32 v76, vcc, 0x20000, v72
	v_lshl_add_u64 v[80:81], v[86:87], 0, s[4:5]
	s_nop 0
	v_addc_co_u32_e32 v77, vcc, 0, v73, vcc
	global_load_dwordx4 v[72:75], v[72:73], off
	s_nop 0
	global_load_dwordx4 v[76:79], v[76:77], off
	v_cndmask_b32_e64 v2, 0, 1, s[12:13]
	global_load_dwordx4 v[80:83], v[80:81], off
	v_cmp_ne_u32_e64 s[4:5], 1, v2
	s_andn2_b64 vcc, exec, s[12:13]
	s_waitcnt vmcnt(11)
	ds_write_b128 v90, v[36:39] offset:27648
	s_waitcnt vmcnt(10)
	ds_write_b128 v90, v[40:43] offset:36864
	s_waitcnt vmcnt(9)
	ds_write_b128 v90, v[48:51] offset:46080
	s_cbranch_vccnz .LBB0_166
	ds_read_b128 v[94:97], v92
	ds_read_b128 v[98:101], v91 offset:18432
	ds_read_b128 v[102:105], v92 offset:32
	ds_read_b128 v[106:109], v91 offset:18464
	s_waitcnt lgkmcnt(2)
	v_mfma_f32_32x32x16_bf16 v[20:35], v[94:97], v[98:101], v[20:35]
	ds_read_b128 v[98:101], v91 offset:23040
	ds_read_b128 v[110:113], v91 offset:23072
	s_waitcnt lgkmcnt(1)
	v_mfma_f32_32x32x16_bf16 v[4:19], v[94:97], v[98:101], v[4:19]
	v_mfma_f32_32x32x16_bf16 v[20:35], v[102:105], v[106:109], v[20:35]
	s_waitcnt lgkmcnt(0)
	v_mfma_f32_32x32x16_bf16 v[4:19], v[102:105], v[110:113], v[4:19]
	ds_read_b128 v[94:97], v92 offset:64
	ds_read_b128 v[98:101], v91 offset:18496
	ds_read_b128 v[102:105], v92 offset:96
	ds_read_b128 v[106:109], v91 offset:18528
	s_waitcnt lgkmcnt(2)
	v_mfma_f32_32x32x16_bf16 v[20:35], v[94:97], v[98:101], v[20:35]
	ds_read_b128 v[98:101], v91 offset:23104
	ds_read_b128 v[110:113], v91 offset:23136
	s_waitcnt lgkmcnt(1)
	v_mfma_f32_32x32x16_bf16 v[4:19], v[94:97], v[98:101], v[4:19]
	v_mfma_f32_32x32x16_bf16 v[20:35], v[102:105], v[106:109], v[20:35]
	s_waitcnt lgkmcnt(0)
	v_mfma_f32_32x32x16_bf16 v[4:19], v[102:105], v[110:113], v[4:19]
.LBB0_166:
	s_min_u32 s14, s22, 10
	s_lshl_b32 s14, s14, 7
	v_lshl_add_u64 v[36:37], v[84:85], 0, s[14:15]
	v_add_co_u32_e32 v40, vcc, 0x20000, v36
	v_lshl_add_u64 v[48:49], v[86:87], 0, s[14:15]
	s_nop 0
	v_addc_co_u32_e32 v41, vcc, 0, v37, vcc
	s_waitcnt lgkmcnt(0)
	s_barrier
	global_load_dwordx4 v[36:39], v[36:37], off offset:640
	s_nop 0
	global_load_dwordx4 v[40:43], v[40:41], off offset:640
	s_and_b64 vcc, exec, s[4:5]
	global_load_dwordx4 v[48:51], v[48:49], off offset:640
	s_waitcnt vmcnt(11)
	ds_write_b128 v90, v[44:47]
	s_waitcnt vmcnt(9)
	ds_write_b128 v90, v[56:59] offset:9216
	s_waitcnt vmcnt(7)
	ds_write_b128 v90, v[64:67] offset:18432
	s_cbranch_vccnz .LBB0_168
	ds_read_b128 v[94:97], v92 offset:27648
	ds_read_b128 v[98:101], v91 offset:46080
	ds_read_b128 v[102:105], v92 offset:27680
	ds_read_b128 v[106:109], v91 offset:46112
	s_waitcnt lgkmcnt(2)
	v_mfma_f32_32x32x16_bf16 v[20:35], v[94:97], v[98:101], v[20:35]
	ds_read_b128 v[98:101], v91 offset:50688
	ds_read_b128 v[110:113], v91 offset:50720
	s_waitcnt lgkmcnt(1)
	v_mfma_f32_32x32x16_bf16 v[4:19], v[94:97], v[98:101], v[4:19]
	v_mfma_f32_32x32x16_bf16 v[20:35], v[102:105], v[106:109], v[20:35]
	s_waitcnt lgkmcnt(0)
	v_mfma_f32_32x32x16_bf16 v[4:19], v[102:105], v[110:113], v[4:19]
	ds_read_b128 v[94:97], v92 offset:27712
	ds_read_b128 v[98:101], v91 offset:46144
	ds_read_b128 v[102:105], v92 offset:27744
	ds_read_b128 v[106:109], v91 offset:46176
	s_waitcnt lgkmcnt(2)
	v_mfma_f32_32x32x16_bf16 v[20:35], v[94:97], v[98:101], v[20:35]
	ds_read_b128 v[98:101], v91 offset:50752
	ds_read_b128 v[110:113], v91 offset:50784
	s_waitcnt lgkmcnt(1)
	v_mfma_f32_32x32x16_bf16 v[4:19], v[94:97], v[98:101], v[4:19]
	v_mfma_f32_32x32x16_bf16 v[20:35], v[102:105], v[106:109], v[20:35]
	s_waitcnt lgkmcnt(0)
	v_mfma_f32_32x32x16_bf16 v[4:19], v[102:105], v[110:113], v[4:19]
; #define GS_STEP(RF, RN, t) do { gs_load<ROWS>(RF, ap, bp, K, ((t) + 4 < nkt) ? (t) + 4 : nkt - 1); \
;         if (wave < ROWS / 32) gs_compute<ROWS>(acc0, acc1, lds + ((t) & 1) * BUF, wave, r, h2); \
;         gs_store<ROWS>(RN, lds + (((t) + 1) & 1) * BUF, soff); \
;         __syncthreads(); } while (0)
; template <int ROWS, class Epi> DI void gemm_small_unit(LAS unsigned char* lds, const bf16* A, const bf16* Bt, int K, int m0, int n0, int n1, const Epi& E, int tid_, int wave) {
;     ...
; #pragma unroll 1
;     for (int kt = 0; kt < nkt; kt += 4) { GS_STEP(R0, R1, kt); GS_STEP(R1, R2, kt + 1); GS_STEP(R2, R3, kt + 2); GS_STEP(R3, R0, kt + 3); }
.LBB0_168:
	s_min_u32 s14, s22, 9
	s_lshl_b32 s14, s14, 7
	v_lshl_add_u64 v[44:45], v[84:85], 0, s[14:15]
	v_add_co_u32_e32 v56, vcc, 0x20000, v44
	v_lshl_add_u64 v[64:65], v[86:87], 0, s[14:15]
	s_nop 0
	v_addc_co_u32_e32 v57, vcc, 0, v45, vcc
	s_waitcnt lgkmcnt(0)
	s_barrier
	global_load_dwordx4 v[44:47], v[44:45], off offset:768
	s_nop 0
	global_load_dwordx4 v[56:59], v[56:57], off offset:768
	s_and_b64 vcc, exec, s[4:5]
	global_load_dwordx4 v[64:67], v[64:65], off offset:768
	ds_write_b128 v90, v[52:55] offset:27648
	ds_write_b128 v90, v[60:63] offset:36864
	s_waitcnt vmcnt(9)
	ds_write_b128 v90, v[68:71] offset:46080
	s_cbranch_vccnz .LBB0_170
	ds_read_b128 v[94:97], v92
	ds_read_b128 v[98:101], v91 offset:18432
	ds_read_b128 v[102:105], v92 offset:32
	ds_read_b128 v[106:109], v91 offset:18464
	s_waitcnt lgkmcnt(2)
	v_mfma_f32_32x32x16_bf16 v[20:35], v[94:97], v[98:101], v[20:35]
	ds_read_b128 v[98:101], v91 offset:23040
	ds_read_b128 v[110:113], v91 offset:23072
	s_waitcnt lgkmcnt(1)
	v_mfma_f32_32x32x16_bf16 v[4:19], v[94:97], v[98:101], v[4:19]
	v_mfma_f32_32x32x16_bf16 v[20:35], v[102:105], v[106:109], v[20:35]
	s_waitcnt lgkmcnt(0)
	v_mfma_f32_32x32x16_bf16 v[4:19], v[102:105], v[110:113], v[4:19]
	ds_read_b128 v[94:97], v92 offset:64
	ds_read_b128 v[98:101], v91 offset:18496
	ds_read_b128 v[102:105], v92 offset:96
	ds_read_b128 v[106:109], v91 offset:18528
	s_waitcnt lgkmcnt(2)
	v_mfma_f32_32x32x16_bf16 v[20:35], v[94:97], v[98:101], v[20:35]
	ds_read_b128 v[98:101], v91 offset:23104
	ds_read_b128 v[110:113], v91 offset:23136
	s_waitcnt lgkmcnt(1)
	v_mfma_f32_32x32x16_bf16 v[4:19], v[94:97], v[98:101], v[4:19]
	v_mfma_f32_32x32x16_bf16 v[20:35], v[102:105], v[106:109], v[20:35]
	s_waitcnt lgkmcnt(0)
	v_mfma_f32_32x32x16_bf16 v[4:19], v[102:105], v[110:113], v[4:19]
.LBB0_170:
	s_min_u32 s14, s22, 8
	s_lshl_b32 s14, s14, 7
	v_lshl_add_u64 v[52:53], v[84:85], 0, s[14:15]
	v_add_co_u32_e32 v60, vcc, 0x20000, v52
	v_lshl_add_u64 v[68:69], v[86:87], 0, s[14:15]
	s_nop 0
	v_addc_co_u32_e32 v61, vcc, 0, v53, vcc
	s_waitcnt lgkmcnt(0)
	s_barrier
	global_load_dwordx4 v[52:55], v[52:53], off offset:896
	s_nop 0
	global_load_dwordx4 v[60:63], v[60:61], off offset:896
	s_and_b64 vcc, exec, s[4:5]
	global_load_dwordx4 v[68:71], v[68:69], off offset:896
	s_waitcnt vmcnt(11)
	ds_write_b128 v90, v[72:75]
	s_waitcnt vmcnt(10)
	ds_write_b128 v90, v[76:79] offset:9216
	s_waitcnt vmcnt(9)
	ds_write_b128 v90, v[80:83] offset:18432
	s_cbranch_vccnz .LBB0_163
	ds_read_b128 v[94:97], v92 offset:27648
	ds_read_b128 v[98:101], v91 offset:46080
	ds_read_b128 v[102:105], v92 offset:27680
	ds_read_b128 v[106:109], v91 offset:46112
	s_waitcnt lgkmcnt(2)
	v_mfma_f32_32x32x16_bf16 v[20:35], v[94:97], v[98:101], v[20:35]
	ds_read_b128 v[98:101], v91 offset:50688
	ds_read_b128 v[110:113], v91 offset:50720
	s_waitcnt lgkmcnt(1)
	v_mfma_f32_32x32x16_bf16 v[4:19], v[94:97], v[98:101], v[4:19]
	v_mfma_f32_32x32x16_bf16 v[20:35], v[102:105], v[106:109], v[20:35]
	s_waitcnt lgkmcnt(0)
	v_mfma_f32_32x32x16_bf16 v[4:19], v[102:105], v[110:113], v[4:19]
	ds_read_b128 v[94:97], v92 offset:27712
	ds_read_b128 v[98:101], v91 offset:46144
	ds_read_b128 v[102:105], v92 offset:27744
	ds_read_b128 v[106:109], v91 offset:46176
	s_waitcnt lgkmcnt(2)
	v_mfma_f32_32x32x16_bf16 v[20:35], v[94:97], v[98:101], v[20:35]
	ds_read_b128 v[98:101], v91 offset:50752
	ds_read_b128 v[110:113], v91 offset:50784
	s_waitcnt lgkmcnt(1)
	v_mfma_f32_32x32x16_bf16 v[4:19], v[94:97], v[98:101], v[4:19]
	v_mfma_f32_32x32x16_bf16 v[20:35], v[102:105], v[106:109], v[20:35]
	s_waitcnt lgkmcnt(0)
	v_mfma_f32_32x32x16_bf16 v[4:19], v[102:105], v[110:113], v[4:19]
	s_branch .LBB0_163

; #define LAS __attribute__((address_space(3)))
; template <int ROWS> DI void gs_load(GsRegs<ROWS>& R, const bf16* ap, const bf16* bp, int K, int kt) {
; #pragma unroll
;     for (int rep = 0; rep < ROWS / 64; ++rep) R.a[rep] = *(const u32x4*)(ap + (size_t)(64 * rep) * K + kt * 64);
;     R.b = *(const u32x4*)(bp + kt * 64);
; }
; template <int ROWS> DI void gs_store(const GsRegs<ROWS>& R, LAS unsigned char* buf, int soff) {
; #pragma unroll
;     for (int rep = 0; rep < ROWS / 64; ++rep) *(LAS u32x4*)(buf + soff + rep * (64 * GS_LD * 2)) = R.a[rep];
;     *(LAS u32x4*)(buf + ROWS * GS_LD * 2 + soff) = R.b;
; }
; template <int ROWS> DI void gs_compute(f32x16& acc0, f32x16& acc1, const LAS unsigned char* ab, int wave, int r, int h2) {
;     const LAS unsigned char* bb = ab + ROWS * GS_LD * 2;
; #pragma unroll
;     for (int s = 0; s < 4; ++s) {
;         const bf16x8 a = *(const LAS bf16x8*)(ab + ((32 * wave + r) * GS_LD + 16 * s + 8 * h2) * 2);
;         const bf16x8 b0 = *(const LAS bf16x8*)(bb + (r * GS_LD + 16 * s + 8 * h2) * 2), b1 = *(const LAS bf16x8*)(bb + ((32 + r) * GS_LD + 16 * s + 8 * h2) * 2);
;         acc0 = MFMA32(a, b0, acc0); acc1 = MFMA32(a, b1, acc1);
;     }
; }
; template <int ROWS, class Epi> DI void gemm_small_unit(LAS unsigned char* lds, const bf16* A, const bf16* Bt, int K, int m0, int n0, int n1, const Epi& E, int tid_, int wave) {
;     constexpr int BUF = (ROWS + 64) * GS_LD * 2;
;     int tid = tid_; asm volatile("" : "+v"(tid));
;     const int lane = tid & 63, r = lane & 31, h2 = lane >> 5;
;     const int arow = tid >> 3, ck = tid & 7;
;     const bf16* ap = A + (size_t)(m0 + arow) * K + ck * 8;
;     const bf16* bp = Bt + (size_t)(arow < 32 ? n0 + arow : n1 + arow - 32) * K + ck * 8;
;     const int soff = (arow * GS_LD + ck * 8) * 2;
;     f32x16 acc0, acc1;
; #pragma unroll
;     for (int i = 0; i < 16; ++i) { acc0[i] = 0.f; acc1[i] = 0.f; }
;     GsRegs<ROWS> R0, R1, R2, R3;
;     gs_load<ROWS>(R0, ap, bp, K, 0); gs_load<ROWS>(R1, ap, bp, K, 1); gs_load<ROWS>(R2, ap, bp, K, 2); gs_load<ROWS>(R3, ap, bp, K, 3);
;     gs_store<ROWS>(R0, lds, soff);
;     __syncthreads();
;     const int nkt = K >> 6;
;     ...
; #pragma unroll 1
;     for (int kt = 0; kt < nkt; kt += 4) { GS_STEP(R0, R1, kt); GS_STEP(R1, R2, kt + 1); GS_STEP(R2, R3, kt + 2); GS_STEP(R3, R0, kt + 3); }
.LBB0_272:
	s_add_i32 s23, s23, 4
	s_addk_i32 s22, 0x100
	s_and_b64 vcc, exec, s[6:7]
	s_waitcnt lgkmcnt(0)
	s_barrier
	s_cbranch_vccnz .LBB0_281
.LBB0_273:
	s_cmp_gt_u32 s23, 27
	s_cselect_b64 s[6:7], -1, 0
	s_cmp_lt_u32 s23, 28
	s_cselect_b32 s16, s22, 0x7c0
	s_lshl_b64 s[36:37], s[16:17], 1
	v_lshl_add_u64 v[4:5], v[74:75], 0, s[36:37]
	v_lshl_add_u64 v[8:9], v[76:77], 0, s[36:37]
	global_load_dwordx4 v[4:7], v[4:5], off
	s_nop 0
	global_load_dwordx4 v[8:11], v[8:9], off
	s_and_b64 vcc, exec, s[4:5]
	s_waitcnt vmcnt(7)
	ds_write_b128 v80, v[50:53] offset:18432
	s_waitcnt vmcnt(6)
	ds_write_b128 v80, v[54:57] offset:27648
	s_cbranch_vccnz .LBB0_275
	ds_read_b128 v[12:15], v82
	ds_read_b128 v[84:87], v81 offset:9216
	s_waitcnt lgkmcnt(0)
	v_mfma_f32_32x32x16_bf16 v[34:49], v[12:15], v[84:87], v[34:49]
	ds_read_b128 v[84:87], v81 offset:13824
	s_waitcnt lgkmcnt(0)
	v_mfma_f32_32x32x16_bf16 v[18:33], v[12:15], v[84:87], v[18:33]
	ds_read_b128 v[12:15], v82 offset:32
	ds_read_b128 v[84:87], v81 offset:9248
	s_waitcnt lgkmcnt(0)
	v_mfma_f32_32x32x16_bf16 v[34:49], v[12:15], v[84:87], v[34:49]
	ds_read_b128 v[84:87], v81 offset:13856
	s_waitcnt lgkmcnt(0)
	v_mfma_f32_32x32x16_bf16 v[18:33], v[12:15], v[84:87], v[18:33]
	ds_read_b128 v[12:15], v82 offset:64
	ds_read_b128 v[84:87], v81 offset:9280
	s_waitcnt lgkmcnt(0)
	v_mfma_f32_32x32x16_bf16 v[34:49], v[12:15], v[84:87], v[34:49]
	ds_read_b128 v[84:87], v81 offset:13888
	s_waitcnt lgkmcnt(0)
	v_mfma_f32_32x32x16_bf16 v[18:33], v[12:15], v[84:87], v[18:33]
	ds_read_b128 v[12:15], v82 offset:96
	ds_read_b128 v[84:87], v81 offset:9312
	s_waitcnt lgkmcnt(0)
	v_mfma_f32_32x32x16_bf16 v[34:49], v[12:15], v[84:87], v[34:49]
	ds_read_b128 v[84:87], v81 offset:13920
	s_waitcnt lgkmcnt(0)
	v_mfma_f32_32x32x16_bf16 v[18:33], v[12:15], v[84:87], v[18:33]
.LBB0_275:
	s_min_u32 s16, s23, 26
	s_lshl_b32 s16, s16, 7
	v_lshl_add_u64 v[12:13], v[74:75], 0, s[16:17]
	s_waitcnt lgkmcnt(0)
	s_barrier
	v_lshl_add_u64 v[14:15], v[76:77], 0, s[16:17]
	global_load_dwordx4 v[50:53], v[12:13], off offset:640
	global_load_dwordx4 v[54:57], v[14:15], off offset:640
	s_and_b64 vcc, exec, s[4:5]
	s_waitcnt vmcnt(7)
	ds_write_b128 v80, v[58:61]
	s_waitcnt vmcnt(5)
	ds_write_b128 v80, v[66:69] offset:9216
	s_cbranch_vccnz .LBB0_277
	ds_read_b128 v[12:15], v82 offset:18432
	ds_read_b128 v[84:87], v81 offset:27648
	s_waitcnt lgkmcnt(0)
	v_mfma_f32_32x32x16_bf16 v[34:49], v[12:15], v[84:87], v[34:49]
	ds_read_b128 v[84:87], v81 offset:32256
	s_waitcnt lgkmcnt(0)
	v_mfma_f32_32x32x16_bf16 v[18:33], v[12:15], v[84:87], v[18:33]
	ds_read_b128 v[12:15], v82 offset:18464
	ds_read_b128 v[84:87], v81 offset:27680
	s_waitcnt lgkmcnt(0)
	v_mfma_f32_32x32x16_bf16 v[34:49], v[12:15], v[84:87], v[34:49]
	ds_read_b128 v[84:87], v81 offset:32288
	s_waitcnt lgkmcnt(0)
	v_mfma_f32_32x32x16_bf16 v[18:33], v[12:15], v[84:87], v[18:33]
	ds_read_b128 v[12:15], v82 offset:18496
	ds_read_b128 v[84:87], v81 offset:27712
	s_waitcnt lgkmcnt(0)
	v_mfma_f32_32x32x16_bf16 v[34:49], v[12:15], v[84:87], v[34:49]
	ds_read_b128 v[84:87], v81 offset:32320
	s_waitcnt lgkmcnt(0)
	v_mfma_f32_32x32x16_bf16 v[18:33], v[12:15], v[84:87], v[18:33]
	ds_read_b128 v[12:15], v82 offset:18528
	ds_read_b128 v[84:87], v81 offset:27744
	s_waitcnt lgkmcnt(0)
	v_mfma_f32_32x32x16_bf16 v[34:49], v[12:15], v[84:87], v[34:49]
	ds_read_b128 v[84:87], v81 offset:32352
	s_waitcnt lgkmcnt(0)
	v_mfma_f32_32x32x16_bf16 v[18:33], v[12:15], v[84:87], v[18:33]
.LBB0_277:
	s_min_u32 s16, s23, 25
	s_lshl_b32 s16, s16, 7
	v_lshl_add_u64 v[12:13], v[74:75], 0, s[16:17]
	s_waitcnt lgkmcnt(0)
	s_barrier
	v_lshl_add_u64 v[14:15], v[76:77], 0, s[16:17]
	global_load_dwordx4 v[58:61], v[12:13], off offset:768
	global_load_dwordx4 v[66:69], v[14:15], off offset:768
	s_and_b64 vcc, exec, s[4:5]
	ds_write_b128 v80, v[62:65] offset:18432
	s_waitcnt vmcnt(6)
	ds_write_b128 v80, v[70:73] offset:27648
	s_cbranch_vccnz .LBB0_279
	ds_read_b128 v[12:15], v82
	ds_read_b128 v[84:87], v81 offset:9216
	s_waitcnt lgkmcnt(0)
	v_mfma_f32_32x32x16_bf16 v[34:49], v[12:15], v[84:87], v[34:49]
	ds_read_b128 v[84:87], v81 offset:13824
	s_waitcnt lgkmcnt(0)
	v_mfma_f32_32x32x16_bf16 v[18:33], v[12:15], v[84:87], v[18:33]
	ds_read_b128 v[12:15], v82 offset:32
	ds_read_b128 v[84:87], v81 offset:9248
	s_waitcnt lgkmcnt(0)
	v_mfma_f32_32x32x16_bf16 v[34:49], v[12:15], v[84:87], v[34:49]
	ds_read_b128 v[84:87], v81 offset:13856
	s_waitcnt lgkmcnt(0)
	v_mfma_f32_32x32x16_bf16 v[18:33], v[12:15], v[84:87], v[18:33]
	ds_read_b128 v[12:15], v82 offset:64
	ds_read_b128 v[84:87], v81 offset:9280
	s_waitcnt lgkmcnt(0)
	v_mfma_f32_32x32x16_bf16 v[34:49], v[12:15], v[84:87], v[34:49]
	ds_read_b128 v[84:87], v81 offset:13888
	s_waitcnt lgkmcnt(0)
	v_mfma_f32_32x32x16_bf16 v[18:33], v[12:15], v[84:87], v[18:33]
	ds_read_b128 v[12:15], v82 offset:96
	ds_read_b128 v[84:87], v81 offset:9312
	s_waitcnt lgkmcnt(0)
	v_mfma_f32_32x32x16_bf16 v[34:49], v[12:15], v[84:87], v[34:49]
	ds_read_b128 v[84:87], v81 offset:13920
	s_waitcnt lgkmcnt(0)
	v_mfma_f32_32x32x16_bf16 v[18:33], v[12:15], v[84:87], v[18:33]
.LBB0_279:
	s_min_u32 s16, s23, 24
	s_lshl_b32 s16, s16, 7
	v_lshl_add_u64 v[12:13], v[74:75], 0, s[16:17]
	s_waitcnt lgkmcnt(0)
	s_barrier
	v_lshl_add_u64 v[14:15], v[76:77], 0, s[16:17]
	global_load_dwordx4 v[62:65], v[12:13], off offset:896
	global_load_dwordx4 v[70:73], v[14:15], off offset:896
	s_and_b64 vcc, exec, s[4:5]
	s_waitcnt vmcnt(7)
	ds_write_b128 v80, v[4:7]
	s_waitcnt vmcnt(6)
	ds_write_b128 v80, v[8:11] offset:9216
	s_cbranch_vccnz .LBB0_272
	ds_read_b128 v[12:15], v82 offset:18432
	ds_read_b128 v[84:87], v81 offset:27648
	s_waitcnt lgkmcnt(0)
	v_mfma_f32_32x32x16_bf16 v[34:49], v[12:15], v[84:87], v[34:49]
	ds_read_b128 v[84:87], v81 offset:32256
	s_waitcnt lgkmcnt(0)
	v_mfma_f32_32x32x16_bf16 v[18:33], v[12:15], v[84:87], v[18:33]
	ds_read_b128 v[12:15], v82 offset:18464
	ds_read_b128 v[84:87], v81 offset:27680
	s_waitcnt lgkmcnt(0)
	v_mfma_f32_32x32x16_bf16 v[34:49], v[12:15], v[84:87], v[34:49]
	ds_read_b128 v[84:87], v81 offset:32288
	s_waitcnt lgkmcnt(0)
	v_mfma_f32_32x32x16_bf16 v[18:33], v[12:15], v[84:87], v[18:33]
	ds_read_b128 v[12:15], v82 offset:18496
	ds_read_b128 v[84:87], v81 offset:27712
	s_waitcnt lgkmcnt(0)
	v_mfma_f32_32x32x16_bf16 v[34:49], v[12:15], v[84:87], v[34:49]
	ds_read_b128 v[84:87], v81 offset:32320
	s_waitcnt lgkmcnt(0)
	v_mfma_f32_32x32x16_bf16 v[18:33], v[12:15], v[84:87], v[18:33]
	ds_read_b128 v[12:15], v82 offset:18528
	ds_read_b128 v[84:87], v81 offset:27744
	s_waitcnt lgkmcnt(0)
	v_mfma_f32_32x32x16_bf16 v[34:49], v[12:15], v[84:87], v[34:49]
	ds_read_b128 v[84:87], v81 offset:32352
	s_waitcnt lgkmcnt(0)
	v_mfma_f32_32x32x16_bf16 v[18:33], v[12:15], v[84:87], v[18:33]
	s_branch .LBB0_272

; #define LAS __attribute__((address_space(3)))
; template <int ROWS> DI void gs_load(GsRegs<ROWS>& R, const bf16* ap, const bf16* bp, int K, int kt) {
; #pragma unroll
;     for (int rep = 0; rep < ROWS / 64; ++rep) R.a[rep] = *(const u32x4*)(ap + (size_t)(64 * rep) * K + kt * 64);
;     R.b = *(const u32x4*)(bp + kt * 64);
; }
; template <int ROWS> DI void gs_store(const GsRegs<ROWS>& R, LAS unsigned char* buf, int soff) {
; #pragma unroll
;     for (int rep = 0; rep < ROWS / 64; ++rep) *(LAS u32x4*)(buf + soff + rep * (64 * GS_LD * 2)) = R.a[rep];
;     *(LAS u32x4*)(buf + ROWS * GS_LD * 2 + soff) = R.b;
; }
; template <int ROWS> DI void gs_compute(f32x16& acc0, f32x16& acc1, const LAS unsigned char* ab, int wave, int r, int h2) {
;     const LAS unsigned char* bb = ab + ROWS * GS_LD * 2;
; #pragma unroll
;     for (int s = 0; s < 4; ++s) {
;         const bf16x8 a = *(const LAS bf16x8*)(ab + ((32 * wave + r) * GS_LD + 16 * s + 8 * h2) * 2);
;         const bf16x8 b0 = *(const LAS bf16x8*)(bb + (r * GS_LD + 16 * s + 8 * h2) * 2), b1 = *(const LAS bf16x8*)(bb + ((32 + r) * GS_LD + 16 * s + 8 * h2) * 2);
;         acc0 = MFMA32(a, b0, acc0); acc1 = MFMA32(a, b1, acc1);
;     }
; }
; template <int ROWS, class Epi> DI void gemm_small_unit(LAS unsigned char* lds, const bf16* A, const bf16* Bt, int K, int m0, int n0, int n1, const Epi& E, int tid_, int wave) {
;     constexpr int BUF = (ROWS + 64) * GS_LD * 2;
;     int tid = tid_; asm volatile("" : "+v"(tid));
;     const int lane = tid & 63, r = lane & 31, h2 = lane >> 5;
;     const int arow = tid >> 3, ck = tid & 7;
;     const bf16* ap = A + (size_t)(m0 + arow) * K + ck * 8;
;     const bf16* bp = Bt + (size_t)(arow < 32 ? n0 + arow : n1 + arow - 32) * K + ck * 8;
;     const int soff = (arow * GS_LD + ck * 8) * 2;
;     f32x16 acc0, acc1;
; #pragma unroll
;     for (int i = 0; i < 16; ++i) { acc0[i] = 0.f; acc1[i] = 0.f; }
;     GsRegs<ROWS> R0, R1, R2, R3;
;     gs_load<ROWS>(R0, ap, bp, K, 0); gs_load<ROWS>(R1, ap, bp, K, 1); gs_load<ROWS>(R2, ap, bp, K, 2); gs_load<ROWS>(R3, ap, bp, K, 3);
;     gs_store<ROWS>(R0, lds, soff);
;     __syncthreads();
;     const int nkt = K >> 6;
;     ...
; #pragma unroll 1
;     for (int kt = 0; kt < nkt; kt += 4) { GS_STEP(R0, R1, kt); GS_STEP(R1, R2, kt + 1); GS_STEP(R2, R3, kt + 2); GS_STEP(R3, R0, kt + 3); }
.LBB0_386:
	s_add_i32 s34, s34, 4
	s_addk_i32 s23, 0x100
	s_and_b64 vcc, exec, s[18:19]
	s_waitcnt lgkmcnt(0)
	s_barrier
	s_cbranch_vccnz .LBB0_395
.LBB0_387:
	s_cmp_gt_u32 s34, 11
	s_cselect_b64 s[18:19], -1, 0
	s_cmp_lt_u32 s34, 12
	s_cselect_b32 s14, s23, 0x3c0
	s_lshl_b64 s[4:5], s[14:15], 1
	v_lshl_add_u64 v[4:5], v[86:87], 0, s[4:5]
	v_add_co_u32_e32 v8, vcc, 0x20000, v4
	v_lshl_add_u64 v[12:13], v[88:89], 0, s[4:5]
	s_nop 0
	v_addc_co_u32_e32 v9, vcc, 0, v5, vcc
	global_load_dwordx4 v[4:7], v[4:5], off
	s_nop 0
	global_load_dwordx4 v[8:11], v[8:9], off
	v_cndmask_b32_e64 v2, 0, 1, s[12:13]
	global_load_dwordx4 v[12:15], v[12:13], off
	v_cmp_ne_u32_e64 s[4:5], 1, v2
	s_andn2_b64 vcc, exec, s[12:13]
	s_waitcnt vmcnt(11)
	ds_write_b128 v92, v[50:53] offset:27648
	s_waitcnt vmcnt(10)
	ds_write_b128 v92, v[54:57] offset:36864
	s_waitcnt vmcnt(9)
	ds_write_b128 v92, v[62:65] offset:46080
	s_cbranch_vccnz .LBB0_389
	ds_read_b128 v[96:99], v94
	ds_read_b128 v[100:103], v93 offset:18432
	ds_read_b128 v[104:107], v94 offset:32
	ds_read_b128 v[108:111], v93 offset:18464
	s_waitcnt lgkmcnt(2)
	v_mfma_f32_32x32x16_bf16 v[18:33], v[96:99], v[100:103], v[18:33]
	ds_read_b128 v[100:103], v93 offset:23040
	ds_read_b128 v[112:115], v93 offset:23072
	s_waitcnt lgkmcnt(1)
	v_mfma_f32_32x32x16_bf16 v[34:49], v[96:99], v[100:103], v[34:49]
	v_mfma_f32_32x32x16_bf16 v[18:33], v[104:107], v[108:111], v[18:33]
	s_waitcnt lgkmcnt(0)
	v_mfma_f32_32x32x16_bf16 v[34:49], v[104:107], v[112:115], v[34:49]
	ds_read_b128 v[96:99], v94 offset:64
	ds_read_b128 v[100:103], v93 offset:18496
	ds_read_b128 v[104:107], v94 offset:96
	ds_read_b128 v[108:111], v93 offset:18528
	s_waitcnt lgkmcnt(2)
	v_mfma_f32_32x32x16_bf16 v[18:33], v[96:99], v[100:103], v[18:33]
	ds_read_b128 v[100:103], v93 offset:23104
	ds_read_b128 v[112:115], v93 offset:23136
	s_waitcnt lgkmcnt(1)
	v_mfma_f32_32x32x16_bf16 v[34:49], v[96:99], v[100:103], v[34:49]
	v_mfma_f32_32x32x16_bf16 v[18:33], v[104:107], v[108:111], v[18:33]
	s_waitcnt lgkmcnt(0)
	v_mfma_f32_32x32x16_bf16 v[34:49], v[104:107], v[112:115], v[34:49]
.LBB0_389:
	s_min_u32 s14, s34, 10
	s_lshl_b32 s14, s14, 7
	v_lshl_add_u64 v[16:17], v[86:87], 0, s[14:15]
	v_add_co_u32_e32 v54, vcc, 0x20000, v16
	s_waitcnt lgkmcnt(0)
	s_nop 0
	v_addc_co_u32_e32 v55, vcc, 0, v17, vcc
	s_barrier
	global_load_dwordx4 v[50:53], v[16:17], off offset:640
	s_nop 0
	global_load_dwordx4 v[54:57], v[54:55], off offset:640
	v_lshl_add_u64 v[16:17], v[88:89], 0, s[14:15]
	global_load_dwordx4 v[62:65], v[16:17], off offset:640
	s_and_b64 vcc, exec, s[4:5]
	s_waitcnt vmcnt(11)
	ds_write_b128 v92, v[58:61]
	s_waitcnt vmcnt(10)
	ds_write_b128 v92, v[78:81] offset:9216
	s_waitcnt vmcnt(9)
	ds_write_b128 v92, v[70:73] offset:18432
	s_cbranch_vccnz .LBB0_391
	ds_read_b128 v[96:99], v94 offset:27648
	ds_read_b128 v[100:103], v93 offset:46080
	ds_read_b128 v[104:107], v94 offset:27680
	ds_read_b128 v[108:111], v93 offset:46112
	s_waitcnt lgkmcnt(2)
	v_mfma_f32_32x32x16_bf16 v[18:33], v[96:99], v[100:103], v[18:33]
	ds_read_b128 v[100:103], v93 offset:50688
	ds_read_b128 v[112:115], v93 offset:50720
	s_waitcnt lgkmcnt(1)
	v_mfma_f32_32x32x16_bf16 v[34:49], v[96:99], v[100:103], v[34:49]
	v_mfma_f32_32x32x16_bf16 v[18:33], v[104:107], v[108:111], v[18:33]
	s_waitcnt lgkmcnt(0)
	v_mfma_f32_32x32x16_bf16 v[34:49], v[104:107], v[112:115], v[34:49]
	ds_read_b128 v[96:99], v94 offset:27712
	ds_read_b128 v[100:103], v93 offset:46144
	ds_read_b128 v[104:107], v94 offset:27744
	ds_read_b128 v[108:111], v93 offset:46176
	s_waitcnt lgkmcnt(2)
	v_mfma_f32_32x32x16_bf16 v[18:33], v[96:99], v[100:103], v[18:33]
	ds_read_b128 v[100:103], v93 offset:50752
	ds_read_b128 v[112:115], v93 offset:50784
	s_waitcnt lgkmcnt(1)
	v_mfma_f32_32x32x16_bf16 v[34:49], v[96:99], v[100:103], v[34:49]
	v_mfma_f32_32x32x16_bf16 v[18:33], v[104:107], v[108:111], v[18:33]
	s_waitcnt lgkmcnt(0)
	v_mfma_f32_32x32x16_bf16 v[34:49], v[104:107], v[112:115], v[34:49]
; #define GS_STEP(RF, RN, t) do { gs_load<ROWS>(RF, ap, bp, K, ((t) + 4 < nkt) ? (t) + 4 : nkt - 1); \
;         if (wave < ROWS / 32) gs_compute<ROWS>(acc0, acc1, lds + ((t) & 1) * BUF, wave, r, h2); \
;         gs_store<ROWS>(RN, lds + (((t) + 1) & 1) * BUF, soff); \
;         __syncthreads(); } while (0)
; template <int ROWS, class Epi> DI void gemm_small_unit(LAS unsigned char* lds, const bf16* A, const bf16* Bt, int K, int m0, int n0, int n1, const Epi& E, int tid_, int wave) {
;     ...
; #pragma unroll 1
;     for (int kt = 0; kt < nkt; kt += 4) { GS_STEP(R0, R1, kt); GS_STEP(R1, R2, kt + 1); GS_STEP(R2, R3, kt + 2); GS_STEP(R3, R0, kt + 3); }
.LBB0_391:
	s_min_u32 s14, s34, 9
	s_lshl_b32 s14, s14, 7
	v_lshl_add_u64 v[16:17], v[86:87], 0, s[14:15]
	v_add_co_u32_e32 v70, vcc, 0x20000, v16
	s_waitcnt lgkmcnt(0)
	s_barrier
	v_addc_co_u32_e32 v71, vcc, 0, v17, vcc
	global_load_dwordx4 v[58:61], v[16:17], off offset:768
	global_load_dwordx4 v[78:81], v[70:71], off offset:768
	v_lshl_add_u64 v[16:17], v[88:89], 0, s[14:15]
	global_load_dwordx4 v[70:73], v[16:17], off offset:768
	s_and_b64 vcc, exec, s[4:5]
	s_waitcnt vmcnt(11)
	ds_write_b128 v92, v[66:69] offset:27648
	s_waitcnt vmcnt(10)
	ds_write_b128 v92, v[82:85] offset:36864
	s_waitcnt vmcnt(9)
	ds_write_b128 v92, v[74:77] offset:46080
	s_cbranch_vccnz .LBB0_393
	ds_read_b128 v[96:99], v94
	ds_read_b128 v[100:103], v93 offset:18432
	ds_read_b128 v[104:107], v94 offset:32
	ds_read_b128 v[108:111], v93 offset:18464
	s_waitcnt lgkmcnt(2)
	v_mfma_f32_32x32x16_bf16 v[18:33], v[96:99], v[100:103], v[18:33]
	ds_read_b128 v[100:103], v93 offset:23040
	ds_read_b128 v[112:115], v93 offset:23072
	s_waitcnt lgkmcnt(1)
	v_mfma_f32_32x32x16_bf16 v[34:49], v[96:99], v[100:103], v[34:49]
	v_mfma_f32_32x32x16_bf16 v[18:33], v[104:107], v[108:111], v[18:33]
	s_waitcnt lgkmcnt(0)
	v_mfma_f32_32x32x16_bf16 v[34:49], v[104:107], v[112:115], v[34:49]
	ds_read_b128 v[96:99], v94 offset:64
	ds_read_b128 v[100:103], v93 offset:18496
	ds_read_b128 v[104:107], v94 offset:96
	ds_read_b128 v[108:111], v93 offset:18528
	s_waitcnt lgkmcnt(2)
	v_mfma_f32_32x32x16_bf16 v[18:33], v[96:99], v[100:103], v[18:33]
	ds_read_b128 v[100:103], v93 offset:23104
	ds_read_b128 v[112:115], v93 offset:23136
	s_waitcnt lgkmcnt(1)
	v_mfma_f32_32x32x16_bf16 v[34:49], v[96:99], v[100:103], v[34:49]
	v_mfma_f32_32x32x16_bf16 v[18:33], v[104:107], v[108:111], v[18:33]
	s_waitcnt lgkmcnt(0)
	v_mfma_f32_32x32x16_bf16 v[34:49], v[104:107], v[112:115], v[34:49]
.LBB0_393:
	s_min_u32 s14, s34, 8
	s_lshl_b32 s14, s14, 7
	v_lshl_add_u64 v[16:17], v[86:87], 0, s[14:15]
	v_add_co_u32_e32 v74, vcc, 0x20000, v16
	s_waitcnt lgkmcnt(0)
	s_barrier
	v_addc_co_u32_e32 v75, vcc, 0, v17, vcc
	global_load_dwordx4 v[66:69], v[16:17], off offset:896
	global_load_dwordx4 v[82:85], v[74:75], off offset:896
	v_lshl_add_u64 v[16:17], v[88:89], 0, s[14:15]
	global_load_dwordx4 v[74:77], v[16:17], off offset:896
	s_and_b64 vcc, exec, s[4:5]
	s_waitcnt vmcnt(11)
	ds_write_b128 v92, v[4:7]
	s_waitcnt vmcnt(10)
	ds_write_b128 v92, v[8:11] offset:9216
	s_waitcnt vmcnt(9)
	ds_write_b128 v92, v[12:15] offset:18432
	s_cbranch_vccnz .LBB0_386
	ds_read_b128 v[96:99], v94 offset:27648
	ds_read_b128 v[100:103], v93 offset:46080
	ds_read_b128 v[104:107], v94 offset:27680
	ds_read_b128 v[108:111], v93 offset:46112
	s_waitcnt lgkmcnt(2)
	v_mfma_f32_32x32x16_bf16 v[18:33], v[96:99], v[100:103], v[18:33]
	ds_read_b128 v[100:103], v93 offset:50688
	ds_read_b128 v[112:115], v93 offset:50720
	s_waitcnt lgkmcnt(1)
	v_mfma_f32_32x32x16_bf16 v[34:49], v[96:99], v[100:103], v[34:49]
	v_mfma_f32_32x32x16_bf16 v[18:33], v[104:107], v[108:111], v[18:33]
	s_waitcnt lgkmcnt(0)
	v_mfma_f32_32x32x16_bf16 v[34:49], v[104:107], v[112:115], v[34:49]
	ds_read_b128 v[96:99], v94 offset:27712
	ds_read_b128 v[100:103], v93 offset:46144
	ds_read_b128 v[104:107], v94 offset:27744
	ds_read_b128 v[108:111], v93 offset:46176
	s_waitcnt lgkmcnt(2)
	v_mfma_f32_32x32x16_bf16 v[18:33], v[96:99], v[100:103], v[18:33]
	ds_read_b128 v[100:103], v93 offset:50752
	ds_read_b128 v[112:115], v93 offset:50784
	s_waitcnt lgkmcnt(1)
	v_mfma_f32_32x32x16_bf16 v[34:49], v[96:99], v[100:103], v[34:49]
	v_mfma_f32_32x32x16_bf16 v[18:33], v[104:107], v[108:111], v[18:33]
	s_waitcnt lgkmcnt(0)
	v_mfma_f32_32x32x16_bf16 v[34:49], v[104:107], v[112:115], v[34:49]
	s_branch .LBB0_386

; #define LAS __attribute__((address_space(3)))
; template <int ROWS> DI void gs_load(GsRegs<ROWS>& R, const bf16* ap, const bf16* bp, int K, int kt) {
; #pragma unroll
;     for (int rep = 0; rep < ROWS / 64; ++rep) R.a[rep] = *(const u32x4*)(ap + (size_t)(64 * rep) * K + kt * 64);
;     R.b = *(const u32x4*)(bp + kt * 64);
; }
; template <int ROWS> DI void gs_store(const GsRegs<ROWS>& R, LAS unsigned char* buf, int soff) {
; #pragma unroll
;     for (int rep = 0; rep < ROWS / 64; ++rep) *(LAS u32x4*)(buf + soff + rep * (64 * GS_LD * 2)) = R.a[rep];
;     *(LAS u32x4*)(buf + ROWS * GS_LD * 2 + soff) = R.b;
; }
; template <int ROWS> DI void gs_compute(f32x16& acc0, f32x16& acc1, const LAS unsigned char* ab, int wave, int r, int h2) {
;     const LAS unsigned char* bb = ab + ROWS * GS_LD * 2;
; #pragma unroll
;     for (int s = 0; s < 4; ++s) {
;         const bf16x8 a = *(const LAS bf16x8*)(ab + ((32 * wave + r) * GS_LD + 16 * s + 8 * h2) * 2);
;         const bf16x8 b0 = *(const LAS bf16x8*)(bb + (r * GS_LD + 16 * s + 8 * h2) * 2), b1 = *(const LAS bf16x8*)(bb + ((32 + r) * GS_LD + 16 * s + 8 * h2) * 2);
;         acc0 = MFMA32(a, b0, acc0); acc1 = MFMA32(a, b1, acc1);
;     }
; }
; template <int ROWS, class Epi> DI void gemm_small_unit(LAS unsigned char* lds, const bf16* A, const bf16* Bt, int K, int m0, int n0, int n1, const Epi& E, int tid_, int wave) {
;     constexpr int BUF = (ROWS + 64) * GS_LD * 2;
;     int tid = tid_; asm volatile("" : "+v"(tid));
;     const int lane = tid & 63, r = lane & 31, h2 = lane >> 5;
;     const int arow = tid >> 3, ck = tid & 7;
;     const bf16* ap = A + (size_t)(m0 + arow) * K + ck * 8;
;     const bf16* bp = Bt + (size_t)(arow < 32 ? n0 + arow : n1 + arow - 32) * K + ck * 8;
;     const int soff = (arow * GS_LD + ck * 8) * 2;
;     f32x16 acc0, acc1;
; #pragma unroll
;     for (int i = 0; i < 16; ++i) { acc0[i] = 0.f; acc1[i] = 0.f; }
;     GsRegs<ROWS> R0, R1, R2, R3;
;     gs_load<ROWS>(R0, ap, bp, K, 0); gs_load<ROWS>(R1, ap, bp, K, 1); gs_load<ROWS>(R2, ap, bp, K, 2); gs_load<ROWS>(R3, ap, bp, K, 3);
;     gs_store<ROWS>(R0, lds, soff);
;     __syncthreads();
;     const int nkt = K >> 6;
;     ...
; #pragma unroll 1
;     for (int kt = 0; kt < nkt; kt += 4) { GS_STEP(R0, R1, kt); GS_STEP(R1, R2, kt + 1); GS_STEP(R2, R3, kt + 2); GS_STEP(R3, R0, kt + 3); }
.LBB0_836:
	s_add_i32 s21, s21, 4
	s_addk_i32 s20, 0x100
	s_and_b64 vcc, exec, s[16:17]
	s_waitcnt lgkmcnt(0)
	s_barrier
	s_cbranch_vccnz .LBB0_845
.LBB0_837:
	s_cmp_gt_u32 s21, 11
	s_cselect_b64 s[16:17], -1, 0
	s_cmp_lt_u32 s21, 12
	s_cselect_b32 s14, s20, 0x3c0
	s_lshl_b64 s[22:23], s[14:15], 1
	v_lshl_add_u64 v[4:5], v[76:77], 0, s[22:23]
	v_lshl_add_u64 v[8:9], v[78:79], 0, s[22:23]
	global_load_dwordx4 v[4:7], v[4:5], off
	s_nop 0
	global_load_dwordx4 v[8:11], v[8:9], off
	s_and_b64 vcc, exec, s[0:1]
	s_waitcnt vmcnt(7)
	ds_write_b128 v80, v[50:53] offset:18432
	s_waitcnt vmcnt(6)
	ds_write_b128 v80, v[54:57] offset:27648
	s_cbranch_vccnz .LBB0_839
	ds_read_b128 v[12:15], v82
	ds_read_b128 v[84:87], v81 offset:9216
	ds_read_b128 v[88:91], v82 offset:32
	ds_read_b128 v[92:95], v81 offset:9248
	s_waitcnt lgkmcnt(2)
	v_mfma_f32_32x32x16_bf16 v[34:49], v[12:15], v[84:87], v[34:49]
	ds_read_b128 v[84:87], v81 offset:13824
	ds_read_b128 v[96:99], v81 offset:13856
	s_waitcnt lgkmcnt(1)
	v_mfma_f32_32x32x16_bf16 v[18:33], v[12:15], v[84:87], v[18:33]
	v_mfma_f32_32x32x16_bf16 v[34:49], v[88:91], v[92:95], v[34:49]
	s_waitcnt lgkmcnt(0)
	v_mfma_f32_32x32x16_bf16 v[18:33], v[88:91], v[96:99], v[18:33]
	ds_read_b128 v[12:15], v82 offset:64
	ds_read_b128 v[84:87], v81 offset:9280
	ds_read_b128 v[88:91], v82 offset:96
	ds_read_b128 v[92:95], v81 offset:9312
	s_waitcnt lgkmcnt(2)
	v_mfma_f32_32x32x16_bf16 v[34:49], v[12:15], v[84:87], v[34:49]
	ds_read_b128 v[84:87], v81 offset:13888
	ds_read_b128 v[96:99], v81 offset:13920
	s_waitcnt lgkmcnt(1)
	v_mfma_f32_32x32x16_bf16 v[18:33], v[12:15], v[84:87], v[18:33]
	v_mfma_f32_32x32x16_bf16 v[34:49], v[88:91], v[92:95], v[34:49]
	s_waitcnt lgkmcnt(0)
	v_mfma_f32_32x32x16_bf16 v[18:33], v[88:91], v[96:99], v[18:33]
.LBB0_839:
	s_min_u32 s14, s21, 10
	s_lshl_b32 s14, s14, 7
	v_lshl_add_u64 v[12:13], v[76:77], 0, s[14:15]
	s_waitcnt lgkmcnt(0)
	s_barrier
	v_lshl_add_u64 v[14:15], v[78:79], 0, s[14:15]
	global_load_dwordx4 v[50:53], v[12:13], off offset:640
	global_load_dwordx4 v[54:57], v[14:15], off offset:640
	s_and_b64 vcc, exec, s[0:1]
	s_waitcnt vmcnt(7)
	ds_write_b128 v80, v[58:61]
	s_waitcnt vmcnt(5)
	ds_write_b128 v80, v[66:69] offset:9216
	s_cbranch_vccnz .LBB0_841
	ds_read_b128 v[12:15], v82 offset:18432
	ds_read_b128 v[84:87], v81 offset:27648
	ds_read_b128 v[88:91], v82 offset:18464
	ds_read_b128 v[92:95], v81 offset:27680
	s_waitcnt lgkmcnt(2)
	v_mfma_f32_32x32x16_bf16 v[34:49], v[12:15], v[84:87], v[34:49]
	ds_read_b128 v[84:87], v81 offset:32256
	ds_read_b128 v[96:99], v81 offset:32288
	s_waitcnt lgkmcnt(1)
	v_mfma_f32_32x32x16_bf16 v[18:33], v[12:15], v[84:87], v[18:33]
	v_mfma_f32_32x32x16_bf16 v[34:49], v[88:91], v[92:95], v[34:49]
	s_waitcnt lgkmcnt(0)
	v_mfma_f32_32x32x16_bf16 v[18:33], v[88:91], v[96:99], v[18:33]
	ds_read_b128 v[12:15], v82 offset:18496
	ds_read_b128 v[84:87], v81 offset:27712
	ds_read_b128 v[88:91], v82 offset:18528
	ds_read_b128 v[92:95], v81 offset:27744
	s_waitcnt lgkmcnt(2)
	v_mfma_f32_32x32x16_bf16 v[34:49], v[12:15], v[84:87], v[34:49]
	ds_read_b128 v[84:87], v81 offset:32320
	ds_read_b128 v[96:99], v81 offset:32352
	s_waitcnt lgkmcnt(1)
	v_mfma_f32_32x32x16_bf16 v[18:33], v[12:15], v[84:87], v[18:33]
	v_mfma_f32_32x32x16_bf16 v[34:49], v[88:91], v[92:95], v[34:49]
	s_waitcnt lgkmcnt(0)
	v_mfma_f32_32x32x16_bf16 v[18:33], v[88:91], v[96:99], v[18:33]
.LBB0_841:
	s_min_u32 s14, s21, 9
	s_lshl_b32 s14, s14, 7
	v_lshl_add_u64 v[12:13], v[76:77], 0, s[14:15]
	s_waitcnt lgkmcnt(0)
	s_barrier
	v_lshl_add_u64 v[14:15], v[78:79], 0, s[14:15]
	global_load_dwordx4 v[58:61], v[12:13], off offset:768
	global_load_dwordx4 v[66:69], v[14:15], off offset:768
	s_and_b64 vcc, exec, s[0:1]
	ds_write_b128 v80, v[62:65] offset:18432
	s_waitcnt vmcnt(6)
	ds_write_b128 v80, v[70:73] offset:27648
	s_cbranch_vccnz .LBB0_843
	ds_read_b128 v[12:15], v82
	ds_read_b128 v[84:87], v81 offset:9216
	ds_read_b128 v[88:91], v82 offset:32
	ds_read_b128 v[92:95], v81 offset:9248
	s_waitcnt lgkmcnt(2)
	v_mfma_f32_32x32x16_bf16 v[34:49], v[12:15], v[84:87], v[34:49]
	ds_read_b128 v[84:87], v81 offset:13824
	ds_read_b128 v[96:99], v81 offset:13856
	s_waitcnt lgkmcnt(1)
	v_mfma_f32_32x32x16_bf16 v[18:33], v[12:15], v[84:87], v[18:33]
	v_mfma_f32_32x32x16_bf16 v[34:49], v[88:91], v[92:95], v[34:49]
	s_waitcnt lgkmcnt(0)
	v_mfma_f32_32x32x16_bf16 v[18:33], v[88:91], v[96:99], v[18:33]
	ds_read_b128 v[12:15], v82 offset:64
	ds_read_b128 v[84:87], v81 offset:9280
	ds_read_b128 v[88:91], v82 offset:96
	ds_read_b128 v[92:95], v81 offset:9312
	s_waitcnt lgkmcnt(2)
	v_mfma_f32_32x32x16_bf16 v[34:49], v[12:15], v[84:87], v[34:49]
	ds_read_b128 v[84:87], v81 offset:13888
	ds_read_b128 v[96:99], v81 offset:13920
	s_waitcnt lgkmcnt(1)
	v_mfma_f32_32x32x16_bf16 v[18:33], v[12:15], v[84:87], v[18:33]
	v_mfma_f32_32x32x16_bf16 v[34:49], v[88:91], v[92:95], v[34:49]
	s_waitcnt lgkmcnt(0)
	v_mfma_f32_32x32x16_bf16 v[18:33], v[88:91], v[96:99], v[18:33]
.LBB0_843:
	s_min_u32 s14, s21, 8
	s_lshl_b32 s14, s14, 7
	v_lshl_add_u64 v[12:13], v[76:77], 0, s[14:15]
	s_waitcnt lgkmcnt(0)
	s_barrier
	v_lshl_add_u64 v[14:15], v[78:79], 0, s[14:15]
	global_load_dwordx4 v[62:65], v[12:13], off offset:896
	global_load_dwordx4 v[70:73], v[14:15], off offset:896
	s_and_b64 vcc, exec, s[0:1]
	s_waitcnt vmcnt(7)
	ds_write_b128 v80, v[4:7]
	s_waitcnt vmcnt(6)
	ds_write_b128 v80, v[8:11] offset:9216
	s_cbranch_vccnz .LBB0_836
	ds_read_b128 v[12:15], v82 offset:18432
	ds_read_b128 v[84:87], v81 offset:27648
	ds_read_b128 v[88:91], v82 offset:18464
	ds_read_b128 v[92:95], v81 offset:27680
	s_waitcnt lgkmcnt(2)
	v_mfma_f32_32x32x16_bf16 v[34:49], v[12:15], v[84:87], v[34:49]
	ds_read_b128 v[84:87], v81 offset:32256
	ds_read_b128 v[96:99], v81 offset:32288
	s_waitcnt lgkmcnt(1)
	v_mfma_f32_32x32x16_bf16 v[18:33], v[12:15], v[84:87], v[18:33]
	v_mfma_f32_32x32x16_bf16 v[34:49], v[88:91], v[92:95], v[34:49]
	s_waitcnt lgkmcnt(0)
	v_mfma_f32_32x32x16_bf16 v[18:33], v[88:91], v[96:99], v[18:33]
	ds_read_b128 v[12:15], v82 offset:18496
	ds_read_b128 v[84:87], v81 offset:27712
	ds_read_b128 v[88:91], v82 offset:18528
	ds_read_b128 v[92:95], v81 offset:27744
	s_waitcnt lgkmcnt(2)
	v_mfma_f32_32x32x16_bf16 v[34:49], v[12:15], v[84:87], v[34:49]
	ds_read_b128 v[84:87], v81 offset:32320
	ds_read_b128 v[96:99], v81 offset:32352
	s_waitcnt lgkmcnt(1)
	v_mfma_f32_32x32x16_bf16 v[18:33], v[12:15], v[84:87], v[18:33]
	v_mfma_f32_32x32x16_bf16 v[34:49], v[88:91], v[92:95], v[34:49]
	s_waitcnt lgkmcnt(0)
	v_mfma_f32_32x32x16_bf16 v[18:33], v[88:91], v[96:99], v[18:33]
	s_branch .LBB0_836

; #define LAS __attribute__((address_space(3)))
; template <int ROWS> DI void gs_load(GsRegs<ROWS>& R, const bf16* ap, const bf16* bp, int K, int kt) {
; #pragma unroll
;     for (int rep = 0; rep < ROWS / 64; ++rep) R.a[rep] = *(const u32x4*)(ap + (size_t)(64 * rep) * K + kt * 64);
;     R.b = *(const u32x4*)(bp + kt * 64);
; }
; template <int ROWS> DI void gs_store(const GsRegs<ROWS>& R, LAS unsigned char* buf, int soff) {
; #pragma unroll
;     for (int rep = 0; rep < ROWS / 64; ++rep) *(LAS u32x4*)(buf + soff + rep * (64 * GS_LD * 2)) = R.a[rep];
;     *(LAS u32x4*)(buf + ROWS * GS_LD * 2 + soff) = R.b;
; }
; template <int ROWS> DI void gs_compute(f32x16& acc0, f32x16& acc1, const LAS unsigned char* ab, int wave, int r, int h2) {
;     const LAS unsigned char* bb = ab + ROWS * GS_LD * 2;
; #pragma unroll
;     for (int s = 0; s < 4; ++s) {
;         const bf16x8 a = *(const LAS bf16x8*)(ab + ((32 * wave + r) * GS_LD + 16 * s + 8 * h2) * 2);
;         const bf16x8 b0 = *(const LAS bf16x8*)(bb + (r * GS_LD + 16 * s + 8 * h2) * 2), b1 = *(const LAS bf16x8*)(bb + ((32 + r) * GS_LD + 16 * s + 8 * h2) * 2);
;         acc0 = MFMA32(a, b0, acc0); acc1 = MFMA32(a, b1, acc1);
;     }
; }
; template <int ROWS, class Epi> DI void gemm_small_unit(LAS unsigned char* lds, const bf16* A, const bf16* Bt, int K, int m0, int n0, int n1, const Epi& E, int tid_, int wave) {
;     constexpr int BUF = (ROWS + 64) * GS_LD * 2;
;     int tid = tid_; asm volatile("" : "+v"(tid));
;     const int lane = tid & 63, r = lane & 31, h2 = lane >> 5;
;     const int arow = tid >> 3, ck = tid & 7;
;     const bf16* ap = A + (size_t)(m0 + arow) * K + ck * 8;
;     const bf16* bp = Bt + (size_t)(arow < 32 ? n0 + arow : n1 + arow - 32) * K + ck * 8;
;     const int soff = (arow * GS_LD + ck * 8) * 2;
;     f32x16 acc0, acc1;
; #pragma unroll
;     for (int i = 0; i < 16; ++i) { acc0[i] = 0.f; acc1[i] = 0.f; }
;     GsRegs<ROWS> R0, R1, R2, R3;
;     gs_load<ROWS>(R0, ap, bp, K, 0); gs_load<ROWS>(R1, ap, bp, K, 1); gs_load<ROWS>(R2, ap, bp, K, 2); gs_load<ROWS>(R3, ap, bp, K, 3);
;     gs_store<ROWS>(R0, lds, soff);
;     __syncthreads();
;     const int nkt = K >> 6;
;     ...
; #pragma unroll 1
;     for (int kt = 0; kt < nkt; kt += 4) { GS_STEP(R0, R1, kt); GS_STEP(R1, R2, kt + 1); GS_STEP(R2, R3, kt + 2); GS_STEP(R3, R0, kt + 3); }
.LBB0_957:
	s_add_i32 s21, s21, 4
	s_addk_i32 s20, 0x100
	s_and_b64 vcc, exec, s[14:15]
	s_waitcnt lgkmcnt(0)
	s_barrier
	s_cbranch_vccnz .LBB0_966
.LBB0_958:
	s_cmp_gt_u32 s21, 11
	s_cselect_b64 s[14:15], -1, 0
	s_cmp_lt_u32 s21, 12
	s_cselect_b32 s12, s20, 0x3c0
	s_lshl_b64 s[0:1], s[12:13], 1
	v_lshl_add_u64 v[72:73], v[84:85], 0, s[0:1]
	v_add_co_u32_e32 v76, vcc, 0x20000, v72
	v_lshl_add_u64 v[80:81], v[86:87], 0, s[0:1]
	s_nop 0
	v_addc_co_u32_e32 v77, vcc, 0, v73, vcc
	global_load_dwordx4 v[72:75], v[72:73], off
	s_nop 0
	global_load_dwordx4 v[76:79], v[76:77], off
	v_cndmask_b32_e64 v2, 0, 1, s[10:11]
	global_load_dwordx4 v[80:83], v[80:81], off
	v_cmp_ne_u32_e64 s[0:1], 1, v2
	s_andn2_b64 vcc, exec, s[10:11]
	s_waitcnt vmcnt(11)
	ds_write_b128 v90, v[36:39] offset:27648
	s_waitcnt vmcnt(10)
	ds_write_b128 v90, v[40:43] offset:36864
	s_waitcnt vmcnt(9)
	ds_write_b128 v90, v[48:51] offset:46080
	s_cbranch_vccnz .LBB0_960
	ds_read_b128 v[94:97], v92
	ds_read_b128 v[98:101], v91 offset:18432
	ds_read_b128 v[102:105], v92 offset:32
	ds_read_b128 v[106:109], v91 offset:18464
	s_waitcnt lgkmcnt(2)
	v_mfma_f32_32x32x16_bf16 v[20:35], v[94:97], v[98:101], v[20:35]
	ds_read_b128 v[98:101], v91 offset:23040
	ds_read_b128 v[110:113], v91 offset:23072
	s_waitcnt lgkmcnt(1)
	v_mfma_f32_32x32x16_bf16 v[4:19], v[94:97], v[98:101], v[4:19]
	v_mfma_f32_32x32x16_bf16 v[20:35], v[102:105], v[106:109], v[20:35]
	s_waitcnt lgkmcnt(0)
	v_mfma_f32_32x32x16_bf16 v[4:19], v[102:105], v[110:113], v[4:19]
	ds_read_b128 v[94:97], v92 offset:64
	ds_read_b128 v[98:101], v91 offset:18496
	ds_read_b128 v[102:105], v92 offset:96
	ds_read_b128 v[106:109], v91 offset:18528
	s_waitcnt lgkmcnt(2)
	v_mfma_f32_32x32x16_bf16 v[20:35], v[94:97], v[98:101], v[20:35]
	ds_read_b128 v[98:101], v91 offset:23104
	ds_read_b128 v[110:113], v91 offset:23136
	s_waitcnt lgkmcnt(1)
	v_mfma_f32_32x32x16_bf16 v[4:19], v[94:97], v[98:101], v[4:19]
	v_mfma_f32_32x32x16_bf16 v[20:35], v[102:105], v[106:109], v[20:35]
	s_waitcnt lgkmcnt(0)
	v_mfma_f32_32x32x16_bf16 v[4:19], v[102:105], v[110:113], v[4:19]
.LBB0_960:
	s_min_u32 s12, s21, 10
	s_lshl_b32 s12, s12, 7
	v_lshl_add_u64 v[36:37], v[84:85], 0, s[12:13]
	v_add_co_u32_e32 v40, vcc, 0x20000, v36
	v_lshl_add_u64 v[48:49], v[86:87], 0, s[12:13]
	s_nop 0
	v_addc_co_u32_e32 v41, vcc, 0, v37, vcc
	s_waitcnt lgkmcnt(0)
	s_barrier
	global_load_dwordx4 v[36:39], v[36:37], off offset:640
	s_nop 0
	global_load_dwordx4 v[40:43], v[40:41], off offset:640
	s_and_b64 vcc, exec, s[0:1]
	global_load_dwordx4 v[48:51], v[48:49], off offset:640
	s_waitcnt vmcnt(11)
	ds_write_b128 v90, v[44:47]
	s_waitcnt vmcnt(9)
	ds_write_b128 v90, v[56:59] offset:9216
	s_waitcnt vmcnt(7)
	ds_write_b128 v90, v[64:67] offset:18432
	s_cbranch_vccnz .LBB0_962
	ds_read_b128 v[94:97], v92 offset:27648
	ds_read_b128 v[98:101], v91 offset:46080
	ds_read_b128 v[102:105], v92 offset:27680
	ds_read_b128 v[106:109], v91 offset:46112
	s_waitcnt lgkmcnt(2)
	v_mfma_f32_32x32x16_bf16 v[20:35], v[94:97], v[98:101], v[20:35]
	ds_read_b128 v[98:101], v91 offset:50688
	ds_read_b128 v[110:113], v91 offset:50720
	s_waitcnt lgkmcnt(1)
	v_mfma_f32_32x32x16_bf16 v[4:19], v[94:97], v[98:101], v[4:19]
	v_mfma_f32_32x32x16_bf16 v[20:35], v[102:105], v[106:109], v[20:35]
	s_waitcnt lgkmcnt(0)
	v_mfma_f32_32x32x16_bf16 v[4:19], v[102:105], v[110:113], v[4:19]
	ds_read_b128 v[94:97], v92 offset:27712
	ds_read_b128 v[98:101], v91 offset:46144
	ds_read_b128 v[102:105], v92 offset:27744
	ds_read_b128 v[106:109], v91 offset:46176
	s_waitcnt lgkmcnt(2)
	v_mfma_f32_32x32x16_bf16 v[20:35], v[94:97], v[98:101], v[20:35]
	ds_read_b128 v[98:101], v91 offset:50752
	ds_read_b128 v[110:113], v91 offset:50784
	s_waitcnt lgkmcnt(1)
	v_mfma_f32_32x32x16_bf16 v[4:19], v[94:97], v[98:101], v[4:19]
	v_mfma_f32_32x32x16_bf16 v[20:35], v[102:105], v[106:109], v[20:35]
	s_waitcnt lgkmcnt(0)
	v_mfma_f32_32x32x16_bf16 v[4:19], v[102:105], v[110:113], v[4:19]
; #define GS_STEP(RF, RN, t) do { gs_load<ROWS>(RF, ap, bp, K, ((t) + 4 < nkt) ? (t) + 4 : nkt - 1); \
;         if (wave < ROWS / 32) gs_compute<ROWS>(acc0, acc1, lds + ((t) & 1) * BUF, wave, r, h2); \
;         gs_store<ROWS>(RN, lds + (((t) + 1) & 1) * BUF, soff); \
;         __syncthreads(); } while (0)
; template <int ROWS, class Epi> DI void gemm_small_unit(LAS unsigned char* lds, const bf16* A, const bf16* Bt, int K, int m0, int n0, int n1, const Epi& E, int tid_, int wave) {
;     ...
; #pragma unroll 1
;     for (int kt = 0; kt < nkt; kt += 4) { GS_STEP(R0, R1, kt); GS_STEP(R1, R2, kt + 1); GS_STEP(R2, R3, kt + 2); GS_STEP(R3, R0, kt + 3); }
.LBB0_962:
	s_min_u32 s12, s21, 9
	s_lshl_b32 s12, s12, 7
	v_lshl_add_u64 v[44:45], v[84:85], 0, s[12:13]
	v_add_co_u32_e32 v56, vcc, 0x20000, v44
	v_lshl_add_u64 v[64:65], v[86:87], 0, s[12:13]
	s_nop 0
	v_addc_co_u32_e32 v57, vcc, 0, v45, vcc
	s_waitcnt lgkmcnt(0)
	s_barrier
	global_load_dwordx4 v[44:47], v[44:45], off offset:768
	s_nop 0
	global_load_dwordx4 v[56:59], v[56:57], off offset:768
	s_and_b64 vcc, exec, s[0:1]
	global_load_dwordx4 v[64:67], v[64:65], off offset:768
	ds_write_b128 v90, v[52:55] offset:27648
	ds_write_b128 v90, v[60:63] offset:36864
	s_waitcnt vmcnt(9)
	ds_write_b128 v90, v[68:71] offset:46080
	s_cbranch_vccnz .LBB0_964
	ds_read_b128 v[94:97], v92
	ds_read_b128 v[98:101], v91 offset:18432
	ds_read_b128 v[102:105], v92 offset:32
	ds_read_b128 v[106:109], v91 offset:18464
	s_waitcnt lgkmcnt(2)
	v_mfma_f32_32x32x16_bf16 v[20:35], v[94:97], v[98:101], v[20:35]
	ds_read_b128 v[98:101], v91 offset:23040
	ds_read_b128 v[110:113], v91 offset:23072
	s_waitcnt lgkmcnt(1)
	v_mfma_f32_32x32x16_bf16 v[4:19], v[94:97], v[98:101], v[4:19]
	v_mfma_f32_32x32x16_bf16 v[20:35], v[102:105], v[106:109], v[20:35]
	s_waitcnt lgkmcnt(0)
	v_mfma_f32_32x32x16_bf16 v[4:19], v[102:105], v[110:113], v[4:19]
	ds_read_b128 v[94:97], v92 offset:64
	ds_read_b128 v[98:101], v91 offset:18496
	ds_read_b128 v[102:105], v92 offset:96
	ds_read_b128 v[106:109], v91 offset:18528
	s_waitcnt lgkmcnt(2)
	v_mfma_f32_32x32x16_bf16 v[20:35], v[94:97], v[98:101], v[20:35]
	ds_read_b128 v[98:101], v91 offset:23104
	ds_read_b128 v[110:113], v91 offset:23136
	s_waitcnt lgkmcnt(1)
	v_mfma_f32_32x32x16_bf16 v[4:19], v[94:97], v[98:101], v[4:19]
	v_mfma_f32_32x32x16_bf16 v[20:35], v[102:105], v[106:109], v[20:35]
	s_waitcnt lgkmcnt(0)
	v_mfma_f32_32x32x16_bf16 v[4:19], v[102:105], v[110:113], v[4:19]
.LBB0_964:
	s_min_u32 s12, s21, 8
	s_lshl_b32 s12, s12, 7
	v_lshl_add_u64 v[52:53], v[84:85], 0, s[12:13]
	v_add_co_u32_e32 v60, vcc, 0x20000, v52
	v_lshl_add_u64 v[68:69], v[86:87], 0, s[12:13]
	s_nop 0
	v_addc_co_u32_e32 v61, vcc, 0, v53, vcc
	s_waitcnt lgkmcnt(0)
	s_barrier
	global_load_dwordx4 v[52:55], v[52:53], off offset:896
	s_nop 0
	global_load_dwordx4 v[60:63], v[60:61], off offset:896
	s_and_b64 vcc, exec, s[0:1]
	global_load_dwordx4 v[68:71], v[68:69], off offset:896
	s_waitcnt vmcnt(11)
	ds_write_b128 v90, v[72:75]
	s_waitcnt vmcnt(10)
	ds_write_b128 v90, v[76:79] offset:9216
	s_waitcnt vmcnt(9)
	ds_write_b128 v90, v[80:83] offset:18432
	s_cbranch_vccnz .LBB0_957
	ds_read_b128 v[94:97], v92 offset:27648
	ds_read_b128 v[98:101], v91 offset:46080
	ds_read_b128 v[102:105], v92 offset:27680
	ds_read_b128 v[106:109], v91 offset:46112
	s_waitcnt lgkmcnt(2)
	v_mfma_f32_32x32x16_bf16 v[20:35], v[94:97], v[98:101], v[20:35]
	ds_read_b128 v[98:101], v91 offset:50688
	ds_read_b128 v[110:113], v91 offset:50720
	s_waitcnt lgkmcnt(1)
	v_mfma_f32_32x32x16_bf16 v[4:19], v[94:97], v[98:101], v[4:19]
	v_mfma_f32_32x32x16_bf16 v[20:35], v[102:105], v[106:109], v[20:35]
	s_waitcnt lgkmcnt(0)
	v_mfma_f32_32x32x16_bf16 v[4:19], v[102:105], v[110:113], v[4:19]
	ds_read_b128 v[94:97], v92 offset:27712
	ds_read_b128 v[98:101], v91 offset:46144
	ds_read_b128 v[102:105], v92 offset:27744
	ds_read_b128 v[106:109], v91 offset:46176
	s_waitcnt lgkmcnt(2)
	v_mfma_f32_32x32x16_bf16 v[20:35], v[94:97], v[98:101], v[20:35]
	ds_read_b128 v[98:101], v91 offset:50752
	ds_read_b128 v[110:113], v91 offset:50784
	s_waitcnt lgkmcnt(1)
	v_mfma_f32_32x32x16_bf16 v[4:19], v[94:97], v[98:101], v[4:19]
	v_mfma_f32_32x32x16_bf16 v[20:35], v[102:105], v[106:109], v[20:35]
	s_waitcnt lgkmcnt(0)
	v_mfma_f32_32x32x16_bf16 v[4:19], v[102:105], v[110:113], v[4:19]
	s_branch .LBB0_957

; #define LAS __attribute__((address_space(3)))
; template <int ROWS> DI void gs_load(GsRegs<ROWS>& R, const bf16* ap, const bf16* bp, int K, int kt) {
; #pragma unroll
;     for (int rep = 0; rep < ROWS / 64; ++rep) R.a[rep] = *(const u32x4*)(ap + (size_t)(64 * rep) * K + kt * 64);
;     R.b = *(const u32x4*)(bp + kt * 64);
; }
; template <int ROWS> DI void gs_store(const GsRegs<ROWS>& R, LAS unsigned char* buf, int soff) {
; #pragma unroll
;     for (int rep = 0; rep < ROWS / 64; ++rep) *(LAS u32x4*)(buf + soff + rep * (64 * GS_LD * 2)) = R.a[rep];
;     *(LAS u32x4*)(buf + ROWS * GS_LD * 2 + soff) = R.b;
; }
; template <int ROWS> DI void gs_compute(f32x16& acc0, f32x16& acc1, const LAS unsigned char* ab, int wave, int r, int h2) {
;     const LAS unsigned char* bb = ab + ROWS * GS_LD * 2;
; #pragma unroll
;     for (int s = 0; s < 4; ++s) {
;         const bf16x8 a = *(const LAS bf16x8*)(ab + ((32 * wave + r) * GS_LD + 16 * s + 8 * h2) * 2);
;         const bf16x8 b0 = *(const LAS bf16x8*)(bb + (r * GS_LD + 16 * s + 8 * h2) * 2), b1 = *(const LAS bf16x8*)(bb + ((32 + r) * GS_LD + 16 * s + 8 * h2) * 2);
;         acc0 = MFMA32(a, b0, acc0); acc1 = MFMA32(a, b1, acc1);
;     }
; }
; template <int ROWS, class Epi> DI void gemm_small_unit(LAS unsigned char* lds, const bf16* A, const bf16* Bt, int K, int m0, int n0, int n1, const Epi& E, int tid_, int wave) {
;     constexpr int BUF = (ROWS + 64) * GS_LD * 2;
;     int tid = tid_; asm volatile("" : "+v"(tid));
;     const int lane = tid & 63, r = lane & 31, h2 = lane >> 5;
;     const int arow = tid >> 3, ck = tid & 7;
;     const bf16* ap = A + (size_t)(m0 + arow) * K + ck * 8;
;     const bf16* bp = Bt + (size_t)(arow < 32 ? n0 + arow : n1 + arow - 32) * K + ck * 8;
;     const int soff = (arow * GS_LD + ck * 8) * 2;
;     f32x16 acc0, acc1;
; #pragma unroll
;     for (int i = 0; i < 16; ++i) { acc0[i] = 0.f; acc1[i] = 0.f; }
;     GsRegs<ROWS> R0, R1, R2, R3;
;     gs_load<ROWS>(R0, ap, bp, K, 0); gs_load<ROWS>(R1, ap, bp, K, 1); gs_load<ROWS>(R2, ap, bp, K, 2); gs_load<ROWS>(R3, ap, bp, K, 3);
;     gs_store<ROWS>(R0, lds, soff);
;     __syncthreads();
;     const int nkt = K >> 6;
;     ...
; #pragma unroll 1
;     for (int kt = 0; kt < nkt; kt += 4) { GS_STEP(R0, R1, kt); GS_STEP(R1, R2, kt + 1); GS_STEP(R2, R3, kt + 2); GS_STEP(R3, R0, kt + 3); }
.LBB0_1067:
	s_cmp_gt_u32 s21, 27
	s_cselect_b64 s[16:17], -1, 0
	s_cmp_lt_u32 s21, 28
	s_cselect_b32 s14, s20, 0x7c0
	s_lshl_b64 s[22:23], s[14:15], 1
	v_lshl_add_u64 v[4:5], v[76:77], 0, s[22:23]
	v_lshl_add_u64 v[8:9], v[78:79], 0, s[22:23]
	global_load_dwordx4 v[4:7], v[4:5], off
	s_nop 0
	global_load_dwordx4 v[8:11], v[8:9], off
	s_and_b64 vcc, exec, s[0:1]
	s_waitcnt vmcnt(7)
	ds_write_b128 v80, v[50:53] offset:18432
	s_waitcnt vmcnt(6)
	ds_write_b128 v80, v[54:57] offset:27648
	s_cbranch_vccnz .LBB0_1069
	ds_read_b128 v[12:15], v82
	ds_read_b128 v[84:87], v81 offset:9216
	ds_read_b128 v[88:91], v82 offset:32
	ds_read_b128 v[92:95], v81 offset:9248
	s_waitcnt lgkmcnt(2)
	v_mfma_f32_32x32x16_bf16 v[34:49], v[12:15], v[84:87], v[34:49]
	ds_read_b128 v[84:87], v81 offset:13824
	ds_read_b128 v[96:99], v81 offset:13856
	s_waitcnt lgkmcnt(1)
	v_mfma_f32_32x32x16_bf16 v[18:33], v[12:15], v[84:87], v[18:33]
	v_mfma_f32_32x32x16_bf16 v[34:49], v[88:91], v[92:95], v[34:49]
	s_waitcnt lgkmcnt(0)
	v_mfma_f32_32x32x16_bf16 v[18:33], v[88:91], v[96:99], v[18:33]
	ds_read_b128 v[12:15], v82 offset:64
	ds_read_b128 v[84:87], v81 offset:9280
	ds_read_b128 v[88:91], v82 offset:96
	ds_read_b128 v[92:95], v81 offset:9312
	s_waitcnt lgkmcnt(2)
	v_mfma_f32_32x32x16_bf16 v[34:49], v[12:15], v[84:87], v[34:49]
	ds_read_b128 v[84:87], v81 offset:13888
	ds_read_b128 v[96:99], v81 offset:13920
	s_waitcnt lgkmcnt(1)
	v_mfma_f32_32x32x16_bf16 v[18:33], v[12:15], v[84:87], v[18:33]
	v_mfma_f32_32x32x16_bf16 v[34:49], v[88:91], v[92:95], v[34:49]
	s_waitcnt lgkmcnt(0)
	v_mfma_f32_32x32x16_bf16 v[18:33], v[88:91], v[96:99], v[18:33]
.LBB0_1069:
	s_min_u32 s14, s21, 26
	s_lshl_b32 s14, s14, 7
	v_lshl_add_u64 v[12:13], v[76:77], 0, s[14:15]
	s_waitcnt lgkmcnt(0)
	s_barrier
	v_lshl_add_u64 v[14:15], v[78:79], 0, s[14:15]
	global_load_dwordx4 v[50:53], v[12:13], off offset:640
	global_load_dwordx4 v[54:57], v[14:15], off offset:640
	s_and_b64 vcc, exec, s[0:1]
	s_waitcnt vmcnt(7)
	ds_write_b128 v80, v[58:61]
	s_waitcnt vmcnt(5)
	ds_write_b128 v80, v[66:69] offset:9216
	s_cbranch_vccnz .LBB0_1071
	ds_read_b128 v[12:15], v82 offset:18432
	ds_read_b128 v[84:87], v81 offset:27648
	ds_read_b128 v[88:91], v82 offset:18464
	ds_read_b128 v[92:95], v81 offset:27680
	s_waitcnt lgkmcnt(2)
	v_mfma_f32_32x32x16_bf16 v[34:49], v[12:15], v[84:87], v[34:49]
	ds_read_b128 v[84:87], v81 offset:32256
	ds_read_b128 v[96:99], v81 offset:32288
	s_waitcnt lgkmcnt(1)
	v_mfma_f32_32x32x16_bf16 v[18:33], v[12:15], v[84:87], v[18:33]
	v_mfma_f32_32x32x16_bf16 v[34:49], v[88:91], v[92:95], v[34:49]
	s_waitcnt lgkmcnt(0)
	v_mfma_f32_32x32x16_bf16 v[18:33], v[88:91], v[96:99], v[18:33]
	ds_read_b128 v[12:15], v82 offset:18496
	ds_read_b128 v[84:87], v81 offset:27712
	ds_read_b128 v[88:91], v82 offset:18528
	ds_read_b128 v[92:95], v81 offset:27744
	s_waitcnt lgkmcnt(2)
	v_mfma_f32_32x32x16_bf16 v[34:49], v[12:15], v[84:87], v[34:49]
	ds_read_b128 v[84:87], v81 offset:32320
	ds_read_b128 v[96:99], v81 offset:32352
	s_waitcnt lgkmcnt(1)
	v_mfma_f32_32x32x16_bf16 v[18:33], v[12:15], v[84:87], v[18:33]
	v_mfma_f32_32x32x16_bf16 v[34:49], v[88:91], v[92:95], v[34:49]
	s_waitcnt lgkmcnt(0)
	v_mfma_f32_32x32x16_bf16 v[18:33], v[88:91], v[96:99], v[18:33]
.LBB0_1071:
	s_min_u32 s14, s21, 25
	s_lshl_b32 s14, s14, 7
	v_lshl_add_u64 v[12:13], v[76:77], 0, s[14:15]
	s_waitcnt lgkmcnt(0)
	s_barrier
	v_lshl_add_u64 v[14:15], v[78:79], 0, s[14:15]
	global_load_dwordx4 v[58:61], v[12:13], off offset:768
	global_load_dwordx4 v[66:69], v[14:15], off offset:768
	s_and_b64 vcc, exec, s[0:1]
	ds_write_b128 v80, v[62:65] offset:18432
	s_waitcnt vmcnt(6)
	ds_write_b128 v80, v[70:73] offset:27648
	s_cbranch_vccnz .LBB0_1073
	ds_read_b128 v[12:15], v82
	ds_read_b128 v[84:87], v81 offset:9216
	ds_read_b128 v[88:91], v82 offset:32
	ds_read_b128 v[92:95], v81 offset:9248
	s_waitcnt lgkmcnt(2)
	v_mfma_f32_32x32x16_bf16 v[34:49], v[12:15], v[84:87], v[34:49]
	ds_read_b128 v[84:87], v81 offset:13824
	ds_read_b128 v[96:99], v81 offset:13856
	s_waitcnt lgkmcnt(1)
	v_mfma_f32_32x32x16_bf16 v[18:33], v[12:15], v[84:87], v[18:33]
	v_mfma_f32_32x32x16_bf16 v[34:49], v[88:91], v[92:95], v[34:49]
	s_waitcnt lgkmcnt(0)
	v_mfma_f32_32x32x16_bf16 v[18:33], v[88:91], v[96:99], v[18:33]
	ds_read_b128 v[12:15], v82 offset:64
	ds_read_b128 v[84:87], v81 offset:9280
	ds_read_b128 v[88:91], v82 offset:96
	ds_read_b128 v[92:95], v81 offset:9312
	s_waitcnt lgkmcnt(2)
	v_mfma_f32_32x32x16_bf16 v[34:49], v[12:15], v[84:87], v[34:49]
	ds_read_b128 v[84:87], v81 offset:13888
	ds_read_b128 v[96:99], v81 offset:13920
	s_waitcnt lgkmcnt(1)
	v_mfma_f32_32x32x16_bf16 v[18:33], v[12:15], v[84:87], v[18:33]
	v_mfma_f32_32x32x16_bf16 v[34:49], v[88:91], v[92:95], v[34:49]
	s_waitcnt lgkmcnt(0)
	v_mfma_f32_32x32x16_bf16 v[18:33], v[88:91], v[96:99], v[18:33]
.LBB0_1073:
	s_min_u32 s14, s21, 24
	s_lshl_b32 s14, s14, 7
	v_lshl_add_u64 v[12:13], v[76:77], 0, s[14:15]
	s_waitcnt lgkmcnt(0)
	s_barrier
	v_lshl_add_u64 v[14:15], v[78:79], 0, s[14:15]
	global_load_dwordx4 v[62:65], v[12:13], off offset:896
	global_load_dwordx4 v[70:73], v[14:15], off offset:896
	s_and_b64 vcc, exec, s[0:1]
	s_waitcnt vmcnt(7)
	ds_write_b128 v80, v[4:7]
	s_waitcnt vmcnt(6)
	ds_write_b128 v80, v[8:11] offset:9216
	s_cbranch_vccnz .LBB0_1066
	ds_read_b128 v[12:15], v82 offset:18432
	ds_read_b128 v[84:87], v81 offset:27648
	ds_read_b128 v[88:91], v82 offset:18464
	ds_read_b128 v[92:95], v81 offset:27680
	s_waitcnt lgkmcnt(2)
	v_mfma_f32_32x32x16_bf16 v[34:49], v[12:15], v[84:87], v[34:49]
	ds_read_b128 v[84:87], v81 offset:32256
	ds_read_b128 v[96:99], v81 offset:32288
	s_waitcnt lgkmcnt(1)
	v_mfma_f32_32x32x16_bf16 v[18:33], v[12:15], v[84:87], v[18:33]
	v_mfma_f32_32x32x16_bf16 v[34:49], v[88:91], v[92:95], v[34:49]
	s_waitcnt lgkmcnt(0)
	v_mfma_f32_32x32x16_bf16 v[18:33], v[88:91], v[96:99], v[18:33]
	ds_read_b128 v[12:15], v82 offset:18496
	ds_read_b128 v[84:87], v81 offset:27712
	ds_read_b128 v[88:91], v82 offset:18528
	ds_read_b128 v[92:95], v81 offset:27744
	s_waitcnt lgkmcnt(2)
	v_mfma_f32_32x32x16_bf16 v[34:49], v[12:15], v[84:87], v[34:49]
	ds_read_b128 v[84:87], v81 offset:32320
	ds_read_b128 v[96:99], v81 offset:32352
	s_waitcnt lgkmcnt(1)
	v_mfma_f32_32x32x16_bf16 v[18:33], v[12:15], v[84:87], v[18:33]
	v_mfma_f32_32x32x16_bf16 v[34:49], v[88:91], v[92:95], v[34:49]
	s_waitcnt lgkmcnt(0)
	v_mfma_f32_32x32x16_bf16 v[18:33], v[88:91], v[96:99], v[18:33]
	s_branch .LBB0_1066

; #define LAS __attribute__((address_space(3)))
; template <int ROWS> DI void gs_load(GsRegs<ROWS>& R, const bf16* ap, const bf16* bp, int K, int kt) {
; #pragma unroll
;     for (int rep = 0; rep < ROWS / 64; ++rep) R.a[rep] = *(const u32x4*)(ap + (size_t)(64 * rep) * K + kt * 64);
;     R.b = *(const u32x4*)(bp + kt * 64);
; }
; template <int ROWS> DI void gs_store(const GsRegs<ROWS>& R, LAS unsigned char* buf, int soff) {
; #pragma unroll
;     for (int rep = 0; rep < ROWS / 64; ++rep) *(LAS u32x4*)(buf + soff + rep * (64 * GS_LD * 2)) = R.a[rep];
;     *(LAS u32x4*)(buf + ROWS * GS_LD * 2 + soff) = R.b;
; }
; template <int ROWS> DI void gs_compute(f32x16& acc0, f32x16& acc1, const LAS unsigned char* ab, int wave, int r, int h2) {
;     const LAS unsigned char* bb = ab + ROWS * GS_LD * 2;
; #pragma unroll
;     for (int s = 0; s < 4; ++s) {
;         const bf16x8 a = *(const LAS bf16x8*)(ab + ((32 * wave + r) * GS_LD + 16 * s + 8 * h2) * 2);
;         const bf16x8 b0 = *(const LAS bf16x8*)(bb + (r * GS_LD + 16 * s + 8 * h2) * 2), b1 = *(const LAS bf16x8*)(bb + ((32 + r) * GS_LD + 16 * s + 8 * h2) * 2);
;         acc0 = MFMA32(a, b0, acc0); acc1 = MFMA32(a, b1, acc1);
;     }
; }
; template <int ROWS, class Epi> DI void gemm_small_unit(LAS unsigned char* lds, const bf16* A, const bf16* Bt, int K, int m0, int n0, int n1, const Epi& E, int tid_, int wave) {
;     constexpr int BUF = (ROWS + 64) * GS_LD * 2;
;     int tid = tid_; asm volatile("" : "+v"(tid));
;     const int lane = tid & 63, r = lane & 31, h2 = lane >> 5;
;     const int arow = tid >> 3, ck = tid & 7;
;     const bf16* ap = A + (size_t)(m0 + arow) * K + ck * 8;
;     const bf16* bp = Bt + (size_t)(arow < 32 ? n0 + arow : n1 + arow - 32) * K + ck * 8;
;     const int soff = (arow * GS_LD + ck * 8) * 2;
;     f32x16 acc0, acc1;
; #pragma unroll
;     for (int i = 0; i < 16; ++i) { acc0[i] = 0.f; acc1[i] = 0.f; }
;     GsRegs<ROWS> R0, R1, R2, R3;
;     gs_load<ROWS>(R0, ap, bp, K, 0); gs_load<ROWS>(R1, ap, bp, K, 1); gs_load<ROWS>(R2, ap, bp, K, 2); gs_load<ROWS>(R3, ap, bp, K, 3);
;     gs_store<ROWS>(R0, lds, soff);
;     __syncthreads();
;     const int nkt = K >> 6;
;     ...
; #pragma unroll 1
;     for (int kt = 0; kt < nkt; kt += 4) { GS_STEP(R0, R1, kt); GS_STEP(R1, R2, kt + 1); GS_STEP(R2, R3, kt + 2); GS_STEP(R3, R0, kt + 3); }
.LBB0_1421:
	s_add_i32 s23, s23, 4
	s_addk_i32 s34, 0x100
	s_and_b64 vcc, exec, s[16:17]
	s_waitcnt lgkmcnt(0)
	s_barrier
	s_cbranch_vccnz .LBB0_1430
.LBB0_1422:
	s_cmp_gt_u32 s23, 11
	s_cselect_b64 s[16:17], -1, 0
	s_cmp_lt_u32 s23, 12
	s_cselect_b32 s12, s34, 0x3c0
	s_lshl_b64 s[0:1], s[12:13], 1
	v_lshl_add_u64 v[12:13], v[118:119], 0, s[0:1]
	v_add_co_u32_e32 v8, vcc, s19, v12
	v_cndmask_b32_e64 v2, 0, 1, s[10:11]
	s_nop 0
	v_addc_co_u32_e32 v9, vcc, 0, v13, vcc
	v_add_co_u32_e32 v14, vcc, 0x40000, v12
	global_load_dwordx4 v[4:7], v[12:13], off
	s_nop 0
	global_load_dwordx4 v[8:11], v[8:9], off
	v_addc_co_u32_e32 v15, vcc, 0, v13, vcc
	v_add_co_u32_e32 v16, vcc, 0x60000, v12
	s_nop 1
	v_addc_co_u32_e32 v17, vcc, 0, v13, vcc
	global_load_dwordx4 v[12:15], v[14:15], off
	s_nop 0
	global_load_dwordx4 v[110:113], v[16:17], off
	v_lshl_add_u64 v[16:17], v[120:121], 0, s[0:1]
	global_load_dwordx4 v[114:117], v[16:17], off
	v_cmp_ne_u32_e64 s[0:1], 1, v2
	s_andn2_b64 vcc, exec, s[10:11]
	s_waitcnt vmcnt(19)
	ds_write_b128 v124, v[50:53] offset:46080
	s_waitcnt vmcnt(18)
	ds_write_b128 v124, v[54:57] offset:55296
	s_waitcnt vmcnt(17)
	ds_write_b128 v124, v[66:69] offset:64512
	s_waitcnt vmcnt(16)
	ds_write_b128 v126, v[78:81] offset:27648
	s_cbranch_vccnz .LBB0_1424
	ds_read_b128 v[128:131], v127
	ds_read_b128 v[132:135], v125 offset:36864
	ds_read_b128 v[136:139], v127 offset:32
	ds_read_b128 v[140:143], v125 offset:36896
	s_waitcnt lgkmcnt(2)
	v_mfma_f32_32x32x16_bf16 v[18:33], v[128:131], v[132:135], v[18:33]
	ds_read_b128 v[132:135], v125 offset:41472
	ds_read_b128 v[144:147], v125 offset:41504
	s_waitcnt lgkmcnt(1)
	v_mfma_f32_32x32x16_bf16 v[34:49], v[128:131], v[132:135], v[34:49]
	v_mfma_f32_32x32x16_bf16 v[18:33], v[136:139], v[140:143], v[18:33]
	s_waitcnt lgkmcnt(0)
	v_mfma_f32_32x32x16_bf16 v[34:49], v[136:139], v[144:147], v[34:49]
	ds_read_b128 v[128:131], v127 offset:64
	ds_read_b128 v[132:135], v125 offset:36928
	ds_read_b128 v[136:139], v127 offset:96
	ds_read_b128 v[140:143], v125 offset:36960
	s_waitcnt lgkmcnt(2)
	v_mfma_f32_32x32x16_bf16 v[18:33], v[128:131], v[132:135], v[18:33]
	ds_read_b128 v[132:135], v125 offset:41536
	ds_read_b128 v[144:147], v125 offset:41568
	s_waitcnt lgkmcnt(1)
	v_mfma_f32_32x32x16_bf16 v[34:49], v[128:131], v[132:135], v[34:49]
	v_mfma_f32_32x32x16_bf16 v[18:33], v[136:139], v[140:143], v[18:33]
	s_waitcnt lgkmcnt(0)
	v_mfma_f32_32x32x16_bf16 v[34:49], v[136:139], v[144:147], v[34:49]
.LBB0_1424:
	s_min_u32 s12, s23, 10
	s_lshl_b32 s12, s12, 7
	v_lshl_add_u64 v[66:67], v[118:119], 0, s[12:13]
	v_add_co_u32_e32 v54, vcc, s19, v66
	v_add_u32_e32 v16, 0x14400, v124
	s_nop 0
	v_addc_co_u32_e32 v55, vcc, 0, v67, vcc
	v_add_co_u32_e32 v68, vcc, 0x40000, v66
	s_waitcnt vmcnt(15)
	ds_write_b128 v16, v[82:85]
	v_addc_co_u32_e32 v69, vcc, 0, v67, vcc
	v_add_co_u32_e32 v78, vcc, 0x60000, v66
	v_lshl_add_u64 v[82:83], v[120:121], 0, s[12:13]
	s_nop 0
	v_addc_co_u32_e32 v79, vcc, 0, v67, vcc
	s_waitcnt lgkmcnt(0)
	s_barrier
	global_load_dwordx4 v[50:53], v[66:67], off offset:640
	s_nop 0
	global_load_dwordx4 v[54:57], v[54:55], off offset:640
	s_nop 0
	global_load_dwordx4 v[66:69], v[68:69], off offset:640
	s_nop 0
	global_load_dwordx4 v[78:81], v[78:79], off offset:640
	s_and_b64 vcc, exec, s[0:1]
	global_load_dwordx4 v[82:85], v[82:83], off offset:640
	v_add_u32_e32 v2, 0x14400, v125
	s_waitcnt vmcnt(19)
	ds_write_b128 v124, v[58:61]
	s_waitcnt vmcnt(17)
	ds_write_b128 v124, v[70:73] offset:9216
	s_waitcnt vmcnt(15)
	ds_write_b128 v124, v[86:89] offset:18432
	s_waitcnt vmcnt(11)
	ds_write_b128 v124, v[102:105] offset:27648
	ds_write_b128 v124, v[94:97] offset:36864
	s_cbranch_vccnz .LBB0_1426
	ds_read_b128 v[128:131], v127 offset:46080
	ds_read_b128 v[132:135], v2
	ds_read_b128 v[136:139], v127 offset:46112
	ds_read_b128 v[140:143], v2 offset:32
	s_waitcnt lgkmcnt(2)
	v_mfma_f32_32x32x16_bf16 v[18:33], v[128:131], v[132:135], v[18:33]
	ds_read_b128 v[132:135], v2 offset:4608
	ds_read_b128 v[144:147], v2 offset:4640
	s_waitcnt lgkmcnt(1)
	v_mfma_f32_32x32x16_bf16 v[34:49], v[128:131], v[132:135], v[34:49]
	v_mfma_f32_32x32x16_bf16 v[18:33], v[136:139], v[140:143], v[18:33]
	s_waitcnt lgkmcnt(0)
	v_mfma_f32_32x32x16_bf16 v[34:49], v[136:139], v[144:147], v[34:49]
	ds_read_b128 v[128:131], v127 offset:46144
	ds_read_b128 v[132:135], v2 offset:64
	ds_read_b128 v[136:139], v127 offset:46176
	ds_read_b128 v[140:143], v2 offset:96
	s_waitcnt lgkmcnt(2)
	v_mfma_f32_32x32x16_bf16 v[18:33], v[128:131], v[132:135], v[18:33]
	ds_read_b128 v[132:135], v2 offset:4672
	ds_read_b128 v[144:147], v2 offset:4704
	s_waitcnt lgkmcnt(1)
	v_mfma_f32_32x32x16_bf16 v[34:49], v[128:131], v[132:135], v[34:49]
	v_mfma_f32_32x32x16_bf16 v[18:33], v[136:139], v[140:143], v[18:33]
	s_waitcnt lgkmcnt(0)
	v_mfma_f32_32x32x16_bf16 v[34:49], v[136:139], v[144:147], v[34:49]
; #define GS_STEP(RF, RN, t) do { gs_load<ROWS>(RF, ap, bp, K, ((t) + 4 < nkt) ? (t) + 4 : nkt - 1); \
;         if (wave < ROWS / 32) gs_compute<ROWS>(acc0, acc1, lds + ((t) & 1) * BUF, wave, r, h2); \
;         gs_store<ROWS>(RN, lds + (((t) + 1) & 1) * BUF, soff); \
;         __syncthreads(); } while (0)
; template <int ROWS, class Epi> DI void gemm_small_unit(LAS unsigned char* lds, const bf16* A, const bf16* Bt, int K, int m0, int n0, int n1, const Epi& E, int tid_, int wave) {
;     ...
; #pragma unroll 1
;     for (int kt = 0; kt < nkt; kt += 4) { GS_STEP(R0, R1, kt); GS_STEP(R1, R2, kt + 1); GS_STEP(R2, R3, kt + 2); GS_STEP(R3, R0, kt + 3); }
.LBB0_1426:
	s_min_u32 s12, s23, 9
	s_lshl_b32 s12, s12, 7
	v_lshl_add_u64 v[86:87], v[118:119], 0, s[12:13]
	v_add_co_u32_e32 v70, vcc, 0x20000, v86
	s_waitcnt lgkmcnt(0)
	s_nop 0
	v_addc_co_u32_e32 v71, vcc, 0, v87, vcc
	v_add_co_u32_e32 v88, vcc, 0x40000, v86
	s_barrier
	s_nop 0
	v_addc_co_u32_e32 v89, vcc, 0, v87, vcc
	v_add_co_u32_e32 v94, vcc, 0x60000, v86
	s_nop 1
	v_addc_co_u32_e32 v95, vcc, 0, v87, vcc
	global_load_dwordx4 v[58:61], v[86:87], off offset:768
	s_nop 0
	global_load_dwordx4 v[70:73], v[70:71], off offset:768
	s_nop 0
	global_load_dwordx4 v[86:89], v[88:89], off offset:768
	s_nop 0
	global_load_dwordx4 v[102:105], v[94:95], off offset:768
	v_lshl_add_u64 v[94:95], v[120:121], 0, s[12:13]
	global_load_dwordx4 v[94:97], v[94:95], off offset:768
	s_and_b64 vcc, exec, s[0:1]
	ds_write_b128 v124, v[62:65] offset:46080
	ds_write_b128 v124, v[74:77] offset:55296
	ds_write_b128 v124, v[90:93] offset:64512
	s_waitcnt vmcnt(15)
	ds_write_b128 v126, v[106:109] offset:27648
	ds_write_b128 v16, v[98:101]
	s_cbranch_vccnz .LBB0_1428
	ds_read_b128 v[128:131], v127
	ds_read_b128 v[132:135], v125 offset:36864
	ds_read_b128 v[136:139], v127 offset:32
	ds_read_b128 v[140:143], v125 offset:36896
	s_waitcnt lgkmcnt(2)
	v_mfma_f32_32x32x16_bf16 v[18:33], v[128:131], v[132:135], v[18:33]
	ds_read_b128 v[132:135], v125 offset:41472
	ds_read_b128 v[144:147], v125 offset:41504
	s_waitcnt lgkmcnt(1)
	v_mfma_f32_32x32x16_bf16 v[34:49], v[128:131], v[132:135], v[34:49]
	v_mfma_f32_32x32x16_bf16 v[18:33], v[136:139], v[140:143], v[18:33]
	s_waitcnt lgkmcnt(0)
	v_mfma_f32_32x32x16_bf16 v[34:49], v[136:139], v[144:147], v[34:49]
	ds_read_b128 v[128:131], v127 offset:64
	ds_read_b128 v[132:135], v125 offset:36928
	ds_read_b128 v[136:139], v127 offset:96
	ds_read_b128 v[140:143], v125 offset:36960
	s_waitcnt lgkmcnt(2)
	v_mfma_f32_32x32x16_bf16 v[18:33], v[128:131], v[132:135], v[18:33]
	ds_read_b128 v[132:135], v125 offset:41536
	ds_read_b128 v[144:147], v125 offset:41568
	s_waitcnt lgkmcnt(1)
	v_mfma_f32_32x32x16_bf16 v[34:49], v[128:131], v[132:135], v[34:49]
	v_mfma_f32_32x32x16_bf16 v[18:33], v[136:139], v[140:143], v[18:33]
	s_waitcnt lgkmcnt(0)
	v_mfma_f32_32x32x16_bf16 v[34:49], v[136:139], v[144:147], v[34:49]
.LBB0_1428:
	s_min_u32 s12, s23, 8
	s_lshl_b32 s12, s12, 7
	v_lshl_add_u64 v[16:17], v[118:119], 0, s[12:13]
	v_add_co_u32_e32 v74, vcc, 0x20000, v16
	s_waitcnt lgkmcnt(0)
	s_nop 0
	v_addc_co_u32_e32 v75, vcc, 0, v17, vcc
	v_add_co_u32_e32 v90, vcc, 0x40000, v16
	s_barrier
	s_nop 0
	v_addc_co_u32_e32 v91, vcc, 0, v17, vcc
	global_load_dwordx4 v[62:65], v[16:17], off offset:896
	s_nop 0
	global_load_dwordx4 v[74:77], v[74:75], off offset:896
	v_add_co_u32_e32 v16, vcc, 0x60000, v16
	s_nop 1
	v_addc_co_u32_e32 v17, vcc, 0, v17, vcc
	global_load_dwordx4 v[90:93], v[90:91], off offset:896
	s_nop 0
	global_load_dwordx4 v[106:109], v[16:17], off offset:896
	v_lshl_add_u64 v[16:17], v[120:121], 0, s[12:13]
	global_load_dwordx4 v[98:101], v[16:17], off offset:896
	s_and_b64 vcc, exec, s[0:1]
	s_waitcnt vmcnt(19)
	ds_write_b128 v124, v[4:7]
	s_waitcnt vmcnt(18)
	ds_write_b128 v124, v[8:11] offset:9216
	s_waitcnt vmcnt(17)
	ds_write_b128 v124, v[12:15] offset:18432
	s_waitcnt vmcnt(16)
	ds_write_b128 v124, v[110:113] offset:27648
	s_waitcnt vmcnt(15)
	ds_write_b128 v124, v[114:117] offset:36864
	s_cbranch_vccnz .LBB0_1421
	ds_read_b128 v[128:131], v127 offset:46080
	ds_read_b128 v[132:135], v2
	ds_read_b128 v[136:139], v127 offset:46112
	ds_read_b128 v[140:143], v2 offset:32
	s_waitcnt lgkmcnt(2)
	v_mfma_f32_32x32x16_bf16 v[18:33], v[128:131], v[132:135], v[18:33]
	ds_read_b128 v[132:135], v2 offset:4608
	ds_read_b128 v[144:147], v2 offset:4640
	s_waitcnt lgkmcnt(1)
	v_mfma_f32_32x32x16_bf16 v[34:49], v[128:131], v[132:135], v[34:49]
	v_mfma_f32_32x32x16_bf16 v[18:33], v[136:139], v[140:143], v[18:33]
	s_waitcnt lgkmcnt(0)
	v_mfma_f32_32x32x16_bf16 v[34:49], v[136:139], v[144:147], v[34:49]
	ds_read_b128 v[128:131], v127 offset:46144
	ds_read_b128 v[132:135], v2 offset:64
	ds_read_b128 v[136:139], v127 offset:46176
	ds_read_b128 v[140:143], v2 offset:96
	s_waitcnt lgkmcnt(2)
	v_mfma_f32_32x32x16_bf16 v[18:33], v[128:131], v[132:135], v[18:33]
	ds_read_b128 v[132:135], v2 offset:4672
	ds_read_b128 v[144:147], v2 offset:4704
	s_waitcnt lgkmcnt(1)
	v_mfma_f32_32x32x16_bf16 v[34:49], v[128:131], v[132:135], v[34:49]
	v_mfma_f32_32x32x16_bf16 v[18:33], v[136:139], v[140:143], v[18:33]
	s_waitcnt lgkmcnt(0)
	v_mfma_f32_32x32x16_bf16 v[34:49], v[136:139], v[144:147], v[34:49]
	s_branch .LBB0_1421

; #define LAS __attribute__((address_space(3)))
; #define MFMA32(a, b, c) __builtin_amdgcn_mfma_f32_32x32x16_bf16((a), (b), (c), 0, 0, 0)
; template <int ROWS> DI void gs_load(GsRegs<ROWS>& R, const bf16* ap, const bf16* bp, int K, int kt) {
; #pragma unroll
;     for (int rep = 0; rep < ROWS / 64; ++rep) R.a[rep] = *(const u32x4*)(ap + (size_t)(64 * rep) * K + kt * 64);
;     R.b = *(const u32x4*)(bp + kt * 64);
; }
; template <int ROWS> DI void gs_store(const GsRegs<ROWS>& R, LAS unsigned char* buf, int soff) {
; #pragma unroll
;     for (int rep = 0; rep < ROWS / 64; ++rep) *(LAS u32x4*)(buf + soff + rep * (64 * GS_LD * 2)) = R.a[rep];
;     *(LAS u32x4*)(buf + ROWS * GS_LD * 2 + soff) = R.b;
; }
; template <int ROWS> DI void gs_compute(f32x16& acc0, f32x16& acc1, const LAS unsigned char* ab, int wave, int r, int h2) {
;     const LAS unsigned char* bb = ab + ROWS * GS_LD * 2;
; #pragma unroll
;     for (int s = 0; s < 4; ++s) {
;         const bf16x8 a = *(const LAS bf16x8*)(ab + ((32 * wave + r) * GS_LD + 16 * s + 8 * h2) * 2);
;         const bf16x8 b0 = *(const LAS bf16x8*)(bb + (r * GS_LD + 16 * s + 8 * h2) * 2), b1 = *(const LAS bf16x8*)(bb + ((32 + r) * GS_LD + 16 * s + 8 * h2) * 2);
;         acc0 = MFMA32(a, b0, acc0); acc1 = MFMA32(a, b1, acc1);
;     }
; }
.LBB0_1977:
	s_cmp_gt_u32 s21, 11
	s_cselect_b64 s[16:17], -1, 0
	s_cmp_lt_u32 s21, 12
	s_cselect_b32 s14, s20, 0x3c0
	s_lshl_b64 s[22:23], s[14:15], 1
	v_lshl_add_u64 v[12:13], v[76:77], 0, s[22:23]
	v_lshl_add_u64 v[14:15], v[78:79], 0, s[22:23]
	global_load_dwordx4 v[4:7], v[12:13], off
	global_load_dwordx4 v[8:11], v[14:15], off
	s_and_b64 vcc, exec, s[0:1]
	s_waitcnt vmcnt(7)
	ds_write_b128 v80, v[50:53] offset:18432
	s_waitcnt vmcnt(6)
	ds_write_b128 v80, v[54:57] offset:27648
	s_cbranch_vccnz .LBB0_1979
	ds_read_b128 v[12:15], v82
	ds_read_b128 v[84:87], v81 offset:9216
	ds_read_b128 v[88:91], v82 offset:32
	ds_read_b128 v[92:95], v81 offset:9248
	s_waitcnt lgkmcnt(2)
	v_mfma_f32_32x32x16_bf16 v[34:49], v[12:15], v[84:87], v[34:49]
	ds_read_b128 v[84:87], v81 offset:13824
	ds_read_b128 v[96:99], v81 offset:13856
	s_waitcnt lgkmcnt(1)
	v_mfma_f32_32x32x16_bf16 v[18:33], v[12:15], v[84:87], v[18:33]
	v_mfma_f32_32x32x16_bf16 v[34:49], v[88:91], v[92:95], v[34:49]
	s_waitcnt lgkmcnt(0)
	v_mfma_f32_32x32x16_bf16 v[18:33], v[88:91], v[96:99], v[18:33]
	ds_read_b128 v[12:15], v82 offset:64
	ds_read_b128 v[84:87], v81 offset:9280
	ds_read_b128 v[88:91], v82 offset:96
	ds_read_b128 v[92:95], v81 offset:9312
	s_waitcnt lgkmcnt(2)
	v_mfma_f32_32x32x16_bf16 v[34:49], v[12:15], v[84:87], v[34:49]
	ds_read_b128 v[84:87], v81 offset:13888
	ds_read_b128 v[96:99], v81 offset:13920
	s_waitcnt lgkmcnt(1)
	v_mfma_f32_32x32x16_bf16 v[18:33], v[12:15], v[84:87], v[18:33]
	v_mfma_f32_32x32x16_bf16 v[34:49], v[88:91], v[92:95], v[34:49]
	s_waitcnt lgkmcnt(0)
	v_mfma_f32_32x32x16_bf16 v[18:33], v[88:91], v[96:99], v[18:33]

; #define LAS __attribute__((address_space(3)))
; template <int ROWS> DI void gs_load(GsRegs<ROWS>& R, const bf16* ap, const bf16* bp, int K, int kt) {
; #pragma unroll
;     for (int rep = 0; rep < ROWS / 64; ++rep) R.a[rep] = *(const u32x4*)(ap + (size_t)(64 * rep) * K + kt * 64);
;     R.b = *(const u32x4*)(bp + kt * 64);
; }
; template <int ROWS> DI void gs_store(const GsRegs<ROWS>& R, LAS unsigned char* buf, int soff) {
; #pragma unroll
;     for (int rep = 0; rep < ROWS / 64; ++rep) *(LAS u32x4*)(buf + soff + rep * (64 * GS_LD * 2)) = R.a[rep];
;     *(LAS u32x4*)(buf + ROWS * GS_LD * 2 + soff) = R.b;
; }
; template <int ROWS> DI void gs_compute(f32x16& acc0, f32x16& acc1, const LAS unsigned char* ab, int wave, int r, int h2) {
;     const LAS unsigned char* bb = ab + ROWS * GS_LD * 2;
; #pragma unroll
;     for (int s = 0; s < 4; ++s) {
;         const bf16x8 a = *(const LAS bf16x8*)(ab + ((32 * wave + r) * GS_LD + 16 * s + 8 * h2) * 2);
;         const bf16x8 b0 = *(const LAS bf16x8*)(bb + (r * GS_LD + 16 * s + 8 * h2) * 2), b1 = *(const LAS bf16x8*)(bb + ((32 + r) * GS_LD + 16 * s + 8 * h2) * 2);
;         acc0 = MFMA32(a, b0, acc0); acc1 = MFMA32(a, b1, acc1);
;     }
; }
; template <int ROWS, class Epi> DI void gemm_small_unit(LAS unsigned char* lds, const bf16* A, const bf16* Bt, int K, int m0, int n0, int n1, const Epi& E, int tid_, int wave) {
;     constexpr int BUF = (ROWS + 64) * GS_LD * 2;
;     int tid = tid_; asm volatile("" : "+v"(tid));
;     const int lane = tid & 63, r = lane & 31, h2 = lane >> 5;
;     const int arow = tid >> 3, ck = tid & 7;
;     const bf16* ap = A + (size_t)(m0 + arow) * K + ck * 8;
;     const bf16* bp = Bt + (size_t)(arow < 32 ? n0 + arow : n1 + arow - 32) * K + ck * 8;
;     const int soff = (arow * GS_LD + ck * 8) * 2;
;     f32x16 acc0, acc1;
; #pragma unroll
;     for (int i = 0; i < 16; ++i) { acc0[i] = 0.f; acc1[i] = 0.f; }
;     GsRegs<ROWS> R0, R1, R2, R3;
;     gs_load<ROWS>(R0, ap, bp, K, 0); gs_load<ROWS>(R1, ap, bp, K, 1); gs_load<ROWS>(R2, ap, bp, K, 2); gs_load<ROWS>(R3, ap, bp, K, 3);
;     gs_store<ROWS>(R0, lds, soff);
;     __syncthreads();
;     const int nkt = K >> 6;
;     ...
; #pragma unroll 1
;     for (int kt = 0; kt < nkt; kt += 4) { GS_STEP(R0, R1, kt); GS_STEP(R1, R2, kt + 1); GS_STEP(R2, R3, kt + 2); GS_STEP(R3, R0, kt + 3); }
.LBB0_2098:
	s_cmp_gt_u32 s21, 11
	s_cselect_b64 s[14:15], -1, 0
	s_cmp_lt_u32 s21, 12
	s_cselect_b32 s12, s20, 0x3c0
	s_lshl_b64 s[0:1], s[12:13], 1
	v_lshl_add_u64 v[80:81], v[84:85], 0, s[0:1]
	v_add_co_u32_e32 v82, vcc, 0x20000, v80
	v_cndmask_b32_e64 v2, 0, 1, s[10:11]
	s_nop 0
	v_addc_co_u32_e32 v83, vcc, 0, v81, vcc
	global_load_dwordx4 v[72:75], v[80:81], off
	global_load_dwordx4 v[76:79], v[82:83], off
	v_lshl_add_u64 v[80:81], v[86:87], 0, s[0:1]
	global_load_dwordx4 v[80:83], v[80:81], off
	v_cmp_ne_u32_e64 s[0:1], 1, v2
	s_andn2_b64 vcc, exec, s[10:11]
	s_waitcnt vmcnt(11)
	ds_write_b128 v90, v[36:39] offset:27648
	s_waitcnt vmcnt(10)
	ds_write_b128 v90, v[40:43] offset:36864
	s_waitcnt vmcnt(9)
	ds_write_b128 v90, v[52:55] offset:46080
	s_cbranch_vccnz .LBB0_2100
	ds_read_b128 v[94:97], v92
	ds_read_b128 v[98:101], v91 offset:18432
	ds_read_b128 v[102:105], v92 offset:32
	ds_read_b128 v[106:109], v91 offset:18464
	s_waitcnt lgkmcnt(2)
	v_mfma_f32_32x32x16_bf16 v[20:35], v[94:97], v[98:101], v[20:35]
	ds_read_b128 v[98:101], v91 offset:23040
	ds_read_b128 v[110:113], v91 offset:23072
	s_waitcnt lgkmcnt(1)
	v_mfma_f32_32x32x16_bf16 v[4:19], v[94:97], v[98:101], v[4:19]
	v_mfma_f32_32x32x16_bf16 v[20:35], v[102:105], v[106:109], v[20:35]
	s_waitcnt lgkmcnt(0)
	v_mfma_f32_32x32x16_bf16 v[4:19], v[102:105], v[110:113], v[4:19]
	ds_read_b128 v[94:97], v92 offset:64
	ds_read_b128 v[98:101], v91 offset:18496
	ds_read_b128 v[102:105], v92 offset:96
	ds_read_b128 v[106:109], v91 offset:18528
	s_waitcnt lgkmcnt(2)
	v_mfma_f32_32x32x16_bf16 v[20:35], v[94:97], v[98:101], v[20:35]
	ds_read_b128 v[98:101], v91 offset:23104
	ds_read_b128 v[110:113], v91 offset:23136
	s_waitcnt lgkmcnt(1)
	v_mfma_f32_32x32x16_bf16 v[4:19], v[94:97], v[98:101], v[4:19]
	v_mfma_f32_32x32x16_bf16 v[20:35], v[102:105], v[106:109], v[20:35]
	s_waitcnt lgkmcnt(0)
	v_mfma_f32_32x32x16_bf16 v[4:19], v[102:105], v[110:113], v[4:19]
.LBB0_2100:
	s_min_u32 s12, s21, 10
	s_lshl_b32 s12, s12, 7
	v_lshl_add_u64 v[52:53], v[84:85], 0, s[12:13]
	v_add_co_u32_e32 v54, vcc, 0x20000, v52
	s_waitcnt lgkmcnt(0)
	s_barrier
	v_addc_co_u32_e32 v55, vcc, 0, v53, vcc
	global_load_dwordx4 v[36:39], v[52:53], off offset:640
	global_load_dwordx4 v[40:43], v[54:55], off offset:640
	v_lshl_add_u64 v[52:53], v[86:87], 0, s[12:13]
	global_load_dwordx4 v[52:55], v[52:53], off offset:640
	s_and_b64 vcc, exec, s[0:1]
	s_waitcnt vmcnt(11)
	ds_write_b128 v90, v[44:47]
	s_waitcnt vmcnt(9)
	ds_write_b128 v90, v[56:59] offset:9216
	s_waitcnt vmcnt(7)
	ds_write_b128 v90, v[64:67] offset:18432
	s_cbranch_vccnz .LBB0_2102
	ds_read_b128 v[94:97], v92 offset:27648
	ds_read_b128 v[98:101], v91 offset:46080
	ds_read_b128 v[102:105], v92 offset:27680
	ds_read_b128 v[106:109], v91 offset:46112
	s_waitcnt lgkmcnt(2)
	v_mfma_f32_32x32x16_bf16 v[20:35], v[94:97], v[98:101], v[20:35]
	ds_read_b128 v[98:101], v91 offset:50688
	ds_read_b128 v[110:113], v91 offset:50720
	s_waitcnt lgkmcnt(1)
	v_mfma_f32_32x32x16_bf16 v[4:19], v[94:97], v[98:101], v[4:19]
	v_mfma_f32_32x32x16_bf16 v[20:35], v[102:105], v[106:109], v[20:35]
	s_waitcnt lgkmcnt(0)
	v_mfma_f32_32x32x16_bf16 v[4:19], v[102:105], v[110:113], v[4:19]
	ds_read_b128 v[94:97], v92 offset:27712
	ds_read_b128 v[98:101], v91 offset:46144
	ds_read_b128 v[102:105], v92 offset:27744
	ds_read_b128 v[106:109], v91 offset:46176
	s_waitcnt lgkmcnt(2)
	v_mfma_f32_32x32x16_bf16 v[20:35], v[94:97], v[98:101], v[20:35]
	ds_read_b128 v[98:101], v91 offset:50752
	ds_read_b128 v[110:113], v91 offset:50784
	s_waitcnt lgkmcnt(1)
	v_mfma_f32_32x32x16_bf16 v[4:19], v[94:97], v[98:101], v[4:19]
	v_mfma_f32_32x32x16_bf16 v[20:35], v[102:105], v[106:109], v[20:35]
	s_waitcnt lgkmcnt(0)
	v_mfma_f32_32x32x16_bf16 v[4:19], v[102:105], v[110:113], v[4:19]
; #define GS_STEP(RF, RN, t) do { gs_load<ROWS>(RF, ap, bp, K, ((t) + 4 < nkt) ? (t) + 4 : nkt - 1); \
;         if (wave < ROWS / 32) gs_compute<ROWS>(acc0, acc1, lds + ((t) & 1) * BUF, wave, r, h2); \
;         gs_store<ROWS>(RN, lds + (((t) + 1) & 1) * BUF, soff); \
;         __syncthreads(); } while (0)
; template <int ROWS, class Epi> DI void gemm_small_unit(LAS unsigned char* lds, const bf16* A, const bf16* Bt, int K, int m0, int n0, int n1, const Epi& E, int tid_, int wave) {
;     ...
; #pragma unroll 1
;     for (int kt = 0; kt < nkt; kt += 4) { GS_STEP(R0, R1, kt); GS_STEP(R1, R2, kt + 1); GS_STEP(R2, R3, kt + 2); GS_STEP(R3, R0, kt + 3); }
.LBB0_2102:
	s_min_u32 s12, s21, 9
	s_lshl_b32 s12, s12, 7
	v_lshl_add_u64 v[64:65], v[84:85], 0, s[12:13]
	v_add_co_u32_e32 v66, vcc, 0x20000, v64
	s_waitcnt lgkmcnt(0)
	s_barrier
	v_addc_co_u32_e32 v67, vcc, 0, v65, vcc
	global_load_dwordx4 v[44:47], v[64:65], off offset:768
	global_load_dwordx4 v[56:59], v[66:67], off offset:768
	v_lshl_add_u64 v[64:65], v[86:87], 0, s[12:13]
	global_load_dwordx4 v[64:67], v[64:65], off offset:768
	s_and_b64 vcc, exec, s[0:1]
	ds_write_b128 v90, v[48:51] offset:27648
	ds_write_b128 v90, v[60:63] offset:36864
	s_waitcnt vmcnt(9)
	ds_write_b128 v90, v[68:71] offset:46080
	s_cbranch_vccnz .LBB0_2104
	ds_read_b128 v[94:97], v92
	ds_read_b128 v[98:101], v91 offset:18432
	ds_read_b128 v[102:105], v92 offset:32
	ds_read_b128 v[106:109], v91 offset:18464
	s_waitcnt lgkmcnt(2)
	v_mfma_f32_32x32x16_bf16 v[20:35], v[94:97], v[98:101], v[20:35]
	ds_read_b128 v[98:101], v91 offset:23040
	ds_read_b128 v[110:113], v91 offset:23072
	s_waitcnt lgkmcnt(1)
	v_mfma_f32_32x32x16_bf16 v[4:19], v[94:97], v[98:101], v[4:19]
	v_mfma_f32_32x32x16_bf16 v[20:35], v[102:105], v[106:109], v[20:35]
	s_waitcnt lgkmcnt(0)
	v_mfma_f32_32x32x16_bf16 v[4:19], v[102:105], v[110:113], v[4:19]
	ds_read_b128 v[94:97], v92 offset:64
	ds_read_b128 v[98:101], v91 offset:18496
	ds_read_b128 v[102:105], v92 offset:96
	ds_read_b128 v[106:109], v91 offset:18528
	s_waitcnt lgkmcnt(2)
	v_mfma_f32_32x32x16_bf16 v[20:35], v[94:97], v[98:101], v[20:35]
	ds_read_b128 v[98:101], v91 offset:23104
	ds_read_b128 v[110:113], v91 offset:23136
	s_waitcnt lgkmcnt(1)
	v_mfma_f32_32x32x16_bf16 v[4:19], v[94:97], v[98:101], v[4:19]
	v_mfma_f32_32x32x16_bf16 v[20:35], v[102:105], v[106:109], v[20:35]
	s_waitcnt lgkmcnt(0)
	v_mfma_f32_32x32x16_bf16 v[4:19], v[102:105], v[110:113], v[4:19]
.LBB0_2104:
	s_min_u32 s12, s21, 8
	s_lshl_b32 s12, s12, 7
	v_lshl_add_u64 v[68:69], v[84:85], 0, s[12:13]
	v_add_co_u32_e32 v70, vcc, 0x20000, v68
	s_waitcnt lgkmcnt(0)
	s_barrier
	v_addc_co_u32_e32 v71, vcc, 0, v69, vcc
	global_load_dwordx4 v[48:51], v[68:69], off offset:896
	global_load_dwordx4 v[60:63], v[70:71], off offset:896
	v_lshl_add_u64 v[68:69], v[86:87], 0, s[12:13]
	global_load_dwordx4 v[68:71], v[68:69], off offset:896
	s_and_b64 vcc, exec, s[0:1]
	s_waitcnt vmcnt(11)
	ds_write_b128 v90, v[72:75]
	s_waitcnt vmcnt(10)
	ds_write_b128 v90, v[76:79] offset:9216
	s_waitcnt vmcnt(9)
	ds_write_b128 v90, v[80:83] offset:18432
	s_cbranch_vccnz .LBB0_2097
	ds_read_b128 v[94:97], v92 offset:27648
	ds_read_b128 v[98:101], v91 offset:46080
	ds_read_b128 v[102:105], v92 offset:27680
	ds_read_b128 v[106:109], v91 offset:46112
	s_waitcnt lgkmcnt(2)
	v_mfma_f32_32x32x16_bf16 v[20:35], v[94:97], v[98:101], v[20:35]
	ds_read_b128 v[98:101], v91 offset:50688
	ds_read_b128 v[110:113], v91 offset:50720
	s_waitcnt lgkmcnt(1)
	v_mfma_f32_32x32x16_bf16 v[4:19], v[94:97], v[98:101], v[4:19]
	v_mfma_f32_32x32x16_bf16 v[20:35], v[102:105], v[106:109], v[20:35]
	s_waitcnt lgkmcnt(0)
	v_mfma_f32_32x32x16_bf16 v[4:19], v[102:105], v[110:113], v[4:19]
	ds_read_b128 v[94:97], v92 offset:27712
	ds_read_b128 v[98:101], v91 offset:46144
	ds_read_b128 v[102:105], v92 offset:27744
	ds_read_b128 v[106:109], v91 offset:46176
	s_waitcnt lgkmcnt(2)
	v_mfma_f32_32x32x16_bf16 v[20:35], v[94:97], v[98:101], v[20:35]
	ds_read_b128 v[98:101], v91 offset:50752
	ds_read_b128 v[110:113], v91 offset:50784
	s_waitcnt lgkmcnt(1)
	v_mfma_f32_32x32x16_bf16 v[4:19], v[94:97], v[98:101], v[4:19]
	v_mfma_f32_32x32x16_bf16 v[20:35], v[102:105], v[106:109], v[20:35]
	s_waitcnt lgkmcnt(0)
	v_mfma_f32_32x32x16_bf16 v[4:19], v[102:105], v[110:113], v[4:19]
	s_branch .LBB0_2097

; #define LAS __attribute__((address_space(3)))
; template <int ROWS> DI void gs_load(GsRegs<ROWS>& R, const bf16* ap, const bf16* bp, int K, int kt) {
; #pragma unroll
;     for (int rep = 0; rep < ROWS / 64; ++rep) R.a[rep] = *(const u32x4*)(ap + (size_t)(64 * rep) * K + kt * 64);
;     R.b = *(const u32x4*)(bp + kt * 64);
; }
; template <int ROWS> DI void gs_store(const GsRegs<ROWS>& R, LAS unsigned char* buf, int soff) {
; #pragma unroll
;     for (int rep = 0; rep < ROWS / 64; ++rep) *(LAS u32x4*)(buf + soff + rep * (64 * GS_LD * 2)) = R.a[rep];
;     *(LAS u32x4*)(buf + ROWS * GS_LD * 2 + soff) = R.b;
; }
; template <int ROWS> DI void gs_compute(f32x16& acc0, f32x16& acc1, const LAS unsigned char* ab, int wave, int r, int h2) {
;     const LAS unsigned char* bb = ab + ROWS * GS_LD * 2;
; #pragma unroll
;     for (int s = 0; s < 4; ++s) {
;         const bf16x8 a = *(const LAS bf16x8*)(ab + ((32 * wave + r) * GS_LD + 16 * s + 8 * h2) * 2);
;         const bf16x8 b0 = *(const LAS bf16x8*)(bb + (r * GS_LD + 16 * s + 8 * h2) * 2), b1 = *(const LAS bf16x8*)(bb + ((32 + r) * GS_LD + 16 * s + 8 * h2) * 2);
;         acc0 = MFMA32(a, b0, acc0); acc1 = MFMA32(a, b1, acc1);
;     }
; }
; template <int ROWS, class Epi> DI void gemm_small_unit(LAS unsigned char* lds, const bf16* A, const bf16* Bt, int K, int m0, int n0, int n1, const Epi& E, int tid_, int wave) {
;     constexpr int BUF = (ROWS + 64) * GS_LD * 2;
;     int tid = tid_; asm volatile("" : "+v"(tid));
;     const int lane = tid & 63, r = lane & 31, h2 = lane >> 5;
;     const int arow = tid >> 3, ck = tid & 7;
;     const bf16* ap = A + (size_t)(m0 + arow) * K + ck * 8;
;     const bf16* bp = Bt + (size_t)(arow < 32 ? n0 + arow : n1 + arow - 32) * K + ck * 8;
;     const int soff = (arow * GS_LD + ck * 8) * 2;
;     f32x16 acc0, acc1;
; #pragma unroll
;     for (int i = 0; i < 16; ++i) { acc0[i] = 0.f; acc1[i] = 0.f; }
;     GsRegs<ROWS> R0, R1, R2, R3;
;     gs_load<ROWS>(R0, ap, bp, K, 0); gs_load<ROWS>(R1, ap, bp, K, 1); gs_load<ROWS>(R2, ap, bp, K, 2); gs_load<ROWS>(R3, ap, bp, K, 3);
;     gs_store<ROWS>(R0, lds, soff);
;     __syncthreads();
;     const int nkt = K >> 6;
;     ...
; #pragma unroll 1
;     for (int kt = 0; kt < nkt; kt += 4) { GS_STEP(R0, R1, kt); GS_STEP(R1, R2, kt + 1); GS_STEP(R2, R3, kt + 2); GS_STEP(R3, R0, kt + 3); }
.LBB0_2187:
	s_add_i32 s81, s81, 4
	s_addk_i32 s80, 0x100
	s_and_b64 vcc, exec, s[78:79]
	s_waitcnt lgkmcnt(0)
	s_barrier
	s_cbranch_vccnz .LBB0_2196
.LBB0_2188:
	s_cmp_gt_u32 s81, 27
	s_cselect_b64 s[78:79], -1, 0
	s_cmp_lt_u32 s81, 28
	s_cselect_b32 s10, s80, 0x7c0
	s_lshl_b64 s[82:83], s[10:11], 1
	v_lshl_add_u64 v[4:5], v[74:75], 0, s[82:83]
	v_lshl_add_u64 v[8:9], v[76:77], 0, s[82:83]
	global_load_dwordx4 v[4:7], v[4:5], off
	s_nop 0
	global_load_dwordx4 v[8:11], v[8:9], off
	s_and_b64 vcc, exec, s[0:1]
	s_waitcnt vmcnt(7)
	ds_write_b128 v79, v[50:53] offset:18432
	s_waitcnt vmcnt(6)
	ds_write_b128 v79, v[54:57] offset:27648
	s_cbranch_vccnz .LBB0_2190
	ds_read_b128 v[12:15], v81
	ds_read_b128 v[82:85], v80 offset:9216
	ds_read_b128 v[86:89], v81 offset:32
	ds_read_b128 v[90:93], v80 offset:9248
	s_waitcnt lgkmcnt(2)
	v_mfma_f32_32x32x16_bf16 v[34:49], v[12:15], v[82:85], v[34:49]
	ds_read_b128 v[82:85], v80 offset:13824
	ds_read_b128 v[94:97], v80 offset:13856
	s_waitcnt lgkmcnt(1)
	v_mfma_f32_32x32x16_bf16 v[18:33], v[12:15], v[82:85], v[18:33]
	v_mfma_f32_32x32x16_bf16 v[34:49], v[86:89], v[90:93], v[34:49]
	s_waitcnt lgkmcnt(0)
	v_mfma_f32_32x32x16_bf16 v[18:33], v[86:89], v[94:97], v[18:33]
	ds_read_b128 v[12:15], v81 offset:64
	ds_read_b128 v[82:85], v80 offset:9280
	ds_read_b128 v[86:89], v81 offset:96
	ds_read_b128 v[90:93], v80 offset:9312
	s_waitcnt lgkmcnt(2)
	v_mfma_f32_32x32x16_bf16 v[34:49], v[12:15], v[82:85], v[34:49]
	ds_read_b128 v[82:85], v80 offset:13888
	ds_read_b128 v[94:97], v80 offset:13920
	s_waitcnt lgkmcnt(1)
	v_mfma_f32_32x32x16_bf16 v[18:33], v[12:15], v[82:85], v[18:33]
	v_mfma_f32_32x32x16_bf16 v[34:49], v[86:89], v[90:93], v[34:49]
	s_waitcnt lgkmcnt(0)
	v_mfma_f32_32x32x16_bf16 v[18:33], v[86:89], v[94:97], v[18:33]
.LBB0_2190:
	s_min_u32 s10, s81, 26
	s_lshl_b32 s10, s10, 7
	v_lshl_add_u64 v[12:13], v[74:75], 0, s[10:11]
	s_waitcnt lgkmcnt(0)
	s_barrier
	v_lshl_add_u64 v[14:15], v[76:77], 0, s[10:11]
	global_load_dwordx4 v[50:53], v[12:13], off offset:640
	global_load_dwordx4 v[54:57], v[14:15], off offset:640
	s_and_b64 vcc, exec, s[0:1]
	s_waitcnt vmcnt(7)
	ds_write_b128 v79, v[58:61]
	s_waitcnt vmcnt(5)
	ds_write_b128 v79, v[66:69] offset:9216
	s_cbranch_vccnz .LBB0_2192
	ds_read_b128 v[12:15], v81 offset:18432
	ds_read_b128 v[82:85], v80 offset:27648
	ds_read_b128 v[86:89], v81 offset:18464
	ds_read_b128 v[90:93], v80 offset:27680
	s_waitcnt lgkmcnt(2)
	v_mfma_f32_32x32x16_bf16 v[34:49], v[12:15], v[82:85], v[34:49]
	ds_read_b128 v[82:85], v80 offset:32256
	ds_read_b128 v[94:97], v80 offset:32288
	s_waitcnt lgkmcnt(1)
	v_mfma_f32_32x32x16_bf16 v[18:33], v[12:15], v[82:85], v[18:33]
	v_mfma_f32_32x32x16_bf16 v[34:49], v[86:89], v[90:93], v[34:49]
	s_waitcnt lgkmcnt(0)
	v_mfma_f32_32x32x16_bf16 v[18:33], v[86:89], v[94:97], v[18:33]
	ds_read_b128 v[12:15], v81 offset:18496
	ds_read_b128 v[82:85], v80 offset:27712
	ds_read_b128 v[86:89], v81 offset:18528
	ds_read_b128 v[90:93], v80 offset:27744
	s_waitcnt lgkmcnt(2)
	v_mfma_f32_32x32x16_bf16 v[34:49], v[12:15], v[82:85], v[34:49]
	ds_read_b128 v[82:85], v80 offset:32320
	ds_read_b128 v[94:97], v80 offset:32352
	s_waitcnt lgkmcnt(1)
	v_mfma_f32_32x32x16_bf16 v[18:33], v[12:15], v[82:85], v[18:33]
	v_mfma_f32_32x32x16_bf16 v[34:49], v[86:89], v[90:93], v[34:49]
	s_waitcnt lgkmcnt(0)
	v_mfma_f32_32x32x16_bf16 v[18:33], v[86:89], v[94:97], v[18:33]
.LBB0_2192:
	s_min_u32 s10, s81, 25
	s_lshl_b32 s10, s10, 7
	v_lshl_add_u64 v[12:13], v[74:75], 0, s[10:11]
	s_waitcnt lgkmcnt(0)
	s_barrier
	v_lshl_add_u64 v[14:15], v[76:77], 0, s[10:11]
	global_load_dwordx4 v[58:61], v[12:13], off offset:768
	global_load_dwordx4 v[66:69], v[14:15], off offset:768
	s_and_b64 vcc, exec, s[0:1]
	ds_write_b128 v79, v[62:65] offset:18432
	s_waitcnt vmcnt(6)
	ds_write_b128 v79, v[70:73] offset:27648
	s_cbranch_vccnz .LBB0_2194
	ds_read_b128 v[12:15], v81
	ds_read_b128 v[82:85], v80 offset:9216
	ds_read_b128 v[86:89], v81 offset:32
	ds_read_b128 v[90:93], v80 offset:9248
	s_waitcnt lgkmcnt(2)
	v_mfma_f32_32x32x16_bf16 v[34:49], v[12:15], v[82:85], v[34:49]
	ds_read_b128 v[82:85], v80 offset:13824
	ds_read_b128 v[94:97], v80 offset:13856
	s_waitcnt lgkmcnt(1)
	v_mfma_f32_32x32x16_bf16 v[18:33], v[12:15], v[82:85], v[18:33]
	v_mfma_f32_32x32x16_bf16 v[34:49], v[86:89], v[90:93], v[34:49]
	s_waitcnt lgkmcnt(0)
	v_mfma_f32_32x32x16_bf16 v[18:33], v[86:89], v[94:97], v[18:33]
	ds_read_b128 v[12:15], v81 offset:64
	ds_read_b128 v[82:85], v80 offset:9280
	ds_read_b128 v[86:89], v81 offset:96
	ds_read_b128 v[90:93], v80 offset:9312
	s_waitcnt lgkmcnt(2)
	v_mfma_f32_32x32x16_bf16 v[34:49], v[12:15], v[82:85], v[34:49]
	ds_read_b128 v[82:85], v80 offset:13888
	ds_read_b128 v[94:97], v80 offset:13920
	s_waitcnt lgkmcnt(1)
	v_mfma_f32_32x32x16_bf16 v[18:33], v[12:15], v[82:85], v[18:33]
	v_mfma_f32_32x32x16_bf16 v[34:49], v[86:89], v[90:93], v[34:49]
	s_waitcnt lgkmcnt(0)
	v_mfma_f32_32x32x16_bf16 v[18:33], v[86:89], v[94:97], v[18:33]
.LBB0_2194:
	s_min_u32 s10, s81, 24
	s_lshl_b32 s10, s10, 7
	v_lshl_add_u64 v[12:13], v[74:75], 0, s[10:11]
	s_waitcnt lgkmcnt(0)
	s_barrier
	v_lshl_add_u64 v[14:15], v[76:77], 0, s[10:11]
	global_load_dwordx4 v[62:65], v[12:13], off offset:896
	global_load_dwordx4 v[70:73], v[14:15], off offset:896
	s_and_b64 vcc, exec, s[0:1]
	s_waitcnt vmcnt(7)
	ds_write_b128 v79, v[4:7]
	s_waitcnt vmcnt(6)
	ds_write_b128 v79, v[8:11] offset:9216
	s_cbranch_vccnz .LBB0_2187
	ds_read_b128 v[12:15], v81 offset:18432
	ds_read_b128 v[82:85], v80 offset:27648
	ds_read_b128 v[86:89], v81 offset:18464
	ds_read_b128 v[90:93], v80 offset:27680
	s_waitcnt lgkmcnt(2)
	v_mfma_f32_32x32x16_bf16 v[34:49], v[12:15], v[82:85], v[34:49]
	ds_read_b128 v[82:85], v80 offset:32256
	ds_read_b128 v[94:97], v80 offset:32288
	s_waitcnt lgkmcnt(1)
	v_mfma_f32_32x32x16_bf16 v[18:33], v[12:15], v[82:85], v[18:33]
	v_mfma_f32_32x32x16_bf16 v[34:49], v[86:89], v[90:93], v[34:49]
	s_waitcnt lgkmcnt(0)
	v_mfma_f32_32x32x16_bf16 v[18:33], v[86:89], v[94:97], v[18:33]
	ds_read_b128 v[12:15], v81 offset:18496
	ds_read_b128 v[82:85], v80 offset:27712
	ds_read_b128 v[86:89], v81 offset:18528
	ds_read_b128 v[90:93], v80 offset:27744
	s_waitcnt lgkmcnt(2)
	v_mfma_f32_32x32x16_bf16 v[34:49], v[12:15], v[82:85], v[34:49]
	ds_read_b128 v[82:85], v80 offset:32320
	ds_read_b128 v[94:97], v80 offset:32352
	s_waitcnt lgkmcnt(1)
	v_mfma_f32_32x32x16_bf16 v[18:33], v[12:15], v[82:85], v[18:33]
	v_mfma_f32_32x32x16_bf16 v[34:49], v[86:89], v[90:93], v[34:49]
	s_waitcnt lgkmcnt(0)
	v_mfma_f32_32x32x16_bf16 v[18:33], v[86:89], v[94:97], v[18:33]
	s_branch .LBB0_2187
